# plus: skip the K-loop trailing barrier in a unit's last iteration, last-flag latched in vcc at the loop head
# speedup vs baseline: 1.0051x; 1.0051x over previous
; #define PG8_STAGE(bufoff, gbase, voff) do { _Pragma("unroll") for (int _i = 0; _i < 2; ++_i) \
;         __builtin_amdgcn_global_load_lds((const unsigned*)((const char*)(gbase) + (voff)[_i]), (PG8_LAS unsigned*)(lds + (bufoff) + ldsw + _i * 8192), 16, 0, 0); } while (0)
; #define PG8_LDA(dst, b, h) do { _Pragma("unroll") for (int m = 0; m < 4; ++m) _Pragma("unroll") for (int k = 0; k < 2; ++k) dst[m][k] = *(const PG8_LAS bf16x8*)(lds + PG8_SA(b, h) + aoff + m * 2048 + k * 1024); } while (0)
; #define PG8_LDB(dst, b, h) do { _Pragma("unroll") for (int n = 0; n < 2; ++n) _Pragma("unroll") for (int k = 0; k < 2; ++k) dst[n][k] = *(const PG8_LAS bf16x8*)(lds + PG8_SB(b, h) + boff + n * 2048 + k * 1024); } while (0)
; #define PG8_MMA(ai, bj, At, Bt) do { __builtin_amdgcn_s_setprio(1); _Pragma("unroll") for (int m = 0; m < 4; ++m) _Pragma("unroll") for (int n = 0; n < 2; ++n) _Pragma("unroll") for (int k = 0; k < 2; ++k) \
;         acc[ai][bj][m][n] = __builtin_amdgcn_mfma_f32_16x16x32_bf16(Bt[n][k], At[m][k], acc[ai][bj][m][n], 0, 0, 0); __builtin_amdgcn_s_setprio(0); } while (0)
; #define PG8_WAIT_V(n) asm volatile("s_waitcnt vmcnt(" #n ")" ::: "memory")
; #define PG8_WAIT_L(n) asm volatile("s_waitcnt lgkmcnt(" #n ")" ::: "memory")
; template <class Epi, class Sched, bool ALIGN_EPI = false, bool SP2 = false>
; __device__ __forceinline__ void gemm_phase(PG8_LAS unsigned char* lds, const Gemm g, const Sched& S, const Epi& E) {
;     ...
;             const bool last = (t == nt - 2);
;             const char* a1 = cA + (size_t)(t + 1) * kstep;
;             const char* a2 = last ? nA : cA + (size_t)(t + 2) * kstep; const char* b2 = last ? nB : cB + (size_t)(t + 2) * kstep;
;             const char* a3 = a2 + kstep; const char* b3 = b2 + kstep;
;             if (last && has_next) S.a_ready(nxt);
;             if constexpr (SP2) {
;             PG8_LDB(B0, 0, 0); PG8_LDB(B1, 0, 1); PG8_SCHED; PG8_LDA(At, 0, 0); PG8_STAGE(PG8_SA(1, 1), a1 + hstep, voffA);
;             PG8_WAIT_V(8); PG8_WAIT_L(0); PG8_BAR; PG8_MMA(0, 0, At, B0); PG8_MMA(0, 1, At, B1); PG8_BAR; PG8_SCHED;
;             PG8_LDA(At, 0, 1); PG8_STAGE(PG8_SB(0, 0), b2, voffB); PG8_STAGE(PG8_SB(0, 1), b2 + hstep, voffB); PG8_STAGE(PG8_SA(0, 0), a2, voffA);
;             PG8_WAIT_V(8); PG8_WAIT_L(0); PG8_BAR; PG8_MMA(1, 0, At, B0); PG8_MMA(1, 1, At, B1); PG8_BAR; PG8_SCHED;
.LBB0_63:
	s_add_i32 s66, s46, 2
	s_add_u32 s10, s44, 0x80
	s_addc_u32 s11, s45, 0
	s_add_i32 s67, 0, 0x10000
	s_cmp_eq_u32 s74, s46
	s_cselect_b64 vcc, -1, 0
	s_cselect_b32 s47, s63, s11
	s_cselect_b32 s46, s62, s10
	s_cselect_b32 s79, s65, s20
	s_cselect_b32 s78, s64, s19
	s_add_i32 s10, 0, 0x14000
	v_add_u32_e32 v140, s67, v183
	v_add_u32_e32 v166, s10, v183
	ds_read_b128 v[128:131], v140
	ds_read_b128 v[132:135], v140 offset:1024
	ds_read_b128 v[136:139], v140 offset:2048
	ds_read_b128 v[140:143], v140 offset:3072
	ds_read_b128 v[144:147], v166
	ds_read_b128 v[148:151], v166 offset:1024
	ds_read_b128 v[152:155], v166 offset:2048
	ds_read_b128 v[166:169], v166 offset:3072
	v_lshl_add_u64 v[190:191], s[44:45], 0, v[162:163]
	s_add_i32 m0, s23, 0xc000
	ds_read_b128 v[170:173], v185
	ds_read_b128 v[174:177], v185 offset:1024
	ds_read_b128 v[178:181], v185 offset:2048
	ds_read_b128 v[186:189], v185 offset:3072
	ds_read_b128 v[194:197], v185 offset:4096
	ds_read_b128 v[198:201], v185 offset:5120
	ds_read_b128 v[202:205], v185 offset:6144
	ds_read_b128 v[206:209], v185 offset:7168
	global_load_lds_dwordx4 v[190:191], off
	v_lshl_add_u64 v[190:191], s[44:45], 0, v[164:165]
	s_add_i32 m0, s23, 0xe000
	s_nop 0
	global_load_lds_dwordx4 v[190:191], off
	s_waitcnt vmcnt(8)
	s_waitcnt lgkmcnt(0)
	s_setprio 1
	s_barrier
	v_mfma_f32_16x16x32_bf16 v[124:127], v[128:131], v[170:173], v[124:127]
	v_mfma_f32_16x16x32_bf16 v[120:123], v[136:139], v[170:173], v[120:123]
	v_mfma_f32_16x16x32_bf16 v[108:111], v[128:131], v[178:181], v[108:111]
	v_mfma_f32_16x16x32_bf16 v[104:107], v[136:139], v[178:181], v[104:107]
	v_mfma_f32_16x16x32_bf16 v[92:95], v[128:131], v[194:197], v[92:95]
	v_mfma_f32_16x16x32_bf16 v[88:91], v[136:139], v[194:197], v[88:91]
	v_mfma_f32_16x16x32_bf16 v[76:79], v[128:131], v[202:205], v[76:79]
	v_mfma_f32_16x16x32_bf16 v[72:75], v[136:139], v[202:205], v[72:75]
	v_mfma_f32_16x16x32_bf16 v[124:127], v[132:135], v[174:177], v[124:127]
	v_mfma_f32_16x16x32_bf16 v[120:123], v[140:143], v[174:177], v[120:123]
	v_mfma_f32_16x16x32_bf16 v[108:111], v[132:135], v[186:189], v[108:111]
	v_mfma_f32_16x16x32_bf16 v[104:107], v[140:143], v[186:189], v[104:107]
	v_mfma_f32_16x16x32_bf16 v[92:95], v[132:135], v[198:201], v[92:95]
	v_mfma_f32_16x16x32_bf16 v[88:91], v[140:143], v[198:201], v[88:91]
	v_mfma_f32_16x16x32_bf16 v[76:79], v[132:135], v[206:209], v[76:79]
	v_mfma_f32_16x16x32_bf16 v[72:75], v[140:143], v[206:209], v[72:75]
	s_setprio 0
	s_setprio 1
	v_mfma_f32_16x16x32_bf16 v[116:119], v[144:147], v[170:173], v[116:119]
	v_mfma_f32_16x16x32_bf16 v[112:115], v[152:155], v[170:173], v[112:115]
	v_mfma_f32_16x16x32_bf16 v[100:103], v[144:147], v[178:181], v[100:103]
	v_mfma_f32_16x16x32_bf16 v[96:99], v[152:155], v[178:181], v[96:99]
	v_mfma_f32_16x16x32_bf16 v[84:87], v[144:147], v[194:197], v[84:87]
	v_mfma_f32_16x16x32_bf16 v[80:83], v[152:155], v[194:197], v[80:83]
	v_mfma_f32_16x16x32_bf16 v[68:71], v[144:147], v[202:205], v[68:71]
	v_mfma_f32_16x16x32_bf16 v[64:67], v[152:155], v[202:205], v[64:67]
	v_mfma_f32_16x16x32_bf16 v[116:119], v[148:151], v[174:177], v[116:119]
	v_mfma_f32_16x16x32_bf16 v[112:115], v[166:169], v[174:177], v[112:115]
	v_mfma_f32_16x16x32_bf16 v[100:103], v[148:151], v[186:189], v[100:103]
	v_mfma_f32_16x16x32_bf16 v[96:99], v[166:169], v[186:189], v[96:99]
	v_mfma_f32_16x16x32_bf16 v[84:87], v[148:151], v[198:201], v[84:87]
	v_mfma_f32_16x16x32_bf16 v[80:83], v[166:169], v[198:201], v[80:83]
	v_mfma_f32_16x16x32_bf16 v[68:71], v[148:151], v[206:209], v[68:71]
	v_mfma_f32_16x16x32_bf16 v[64:67], v[166:169], v[206:209], v[64:67]
	s_barrier
	s_setprio 0
	s_add_i32 s11, s67, s22
	v_lshl_add_u64 v[190:191], s[78:79], 0, v[192:193]
	s_mov_b32 m0, s11
	ds_read_b128 v[170:173], v185 offset:16384
	ds_read_b128 v[174:177], v185 offset:17408
	ds_read_b128 v[178:181], v185 offset:18432
	ds_read_b128 v[186:189], v185 offset:19456
	ds_read_b128 v[194:197], v185 offset:20480
	ds_read_b128 v[198:201], v185 offset:21504
	ds_read_b128 v[202:205], v185 offset:22528
	ds_read_b128 v[206:209], v185 offset:23552
	global_load_lds_dwordx4 v[190:191], off
	s_add_i32 m0, s11, 0x2000
	v_lshl_add_u64 v[210:211], s[78:79], 0, v[160:161]
	s_add_u32 s78, s78, s52
	s_addc_u32 s79, s79, 0
	s_add_i32 s10, s10, s22
	global_load_lds_dwordx4 v[210:211], off
	v_lshl_add_u64 v[212:213], s[78:79], 0, v[192:193]
	s_mov_b32 m0, s10
	v_lshl_add_u64 v[214:215], s[78:79], 0, v[160:161]
	global_load_lds_dwordx4 v[212:213], off
	s_add_i32 m0, s10, 0x2000
	v_lshl_add_u64 v[216:217], s[46:47], 0, v[156:157]
	global_load_lds_dwordx4 v[214:215], off
	s_mov_b32 m0, s23
	v_lshl_add_u64 v[218:219], s[46:47], 0, v[158:159]
	global_load_lds_dwordx4 v[216:217], off
	s_mov_b32 m0, s51
	s_nop 0
	global_load_lds_dwordx4 v[218:219], off
	s_waitcnt vmcnt(8)
	s_waitcnt lgkmcnt(0)
	s_setprio 1
	s_barrier
; #define PG8_STAGE(bufoff, gbase, voff) do { _Pragma("unroll") for (int _i = 0; _i < 2; ++_i) \
;         __builtin_amdgcn_global_load_lds((const unsigned*)((const char*)(gbase) + (voff)[_i]), (PG8_LAS unsigned*)(lds + (bufoff) + ldsw + _i * 8192), 16, 0, 0); } while (0)
; #define PG8_LDA(dst, b, h) do { _Pragma("unroll") for (int m = 0; m < 4; ++m) _Pragma("unroll") for (int k = 0; k < 2; ++k) dst[m][k] = *(const PG8_LAS bf16x8*)(lds + PG8_SA(b, h) + aoff + m * 2048 + k * 1024); } while (0)
; #define PG8_LDB(dst, b, h) do { _Pragma("unroll") for (int n = 0; n < 2; ++n) _Pragma("unroll") for (int k = 0; k < 2; ++k) dst[n][k] = *(const PG8_LAS bf16x8*)(lds + PG8_SB(b, h) + boff + n * 2048 + k * 1024); } while (0)
; #define PG8_MMA(ai, bj, At, Bt) do { __builtin_amdgcn_s_setprio(1); _Pragma("unroll") for (int m = 0; m < 4; ++m) _Pragma("unroll") for (int n = 0; n < 2; ++n) _Pragma("unroll") for (int k = 0; k < 2; ++k) \
;         acc[ai][bj][m][n] = __builtin_amdgcn_mfma_f32_16x16x32_bf16(Bt[n][k], At[m][k], acc[ai][bj][m][n], 0, 0, 0); __builtin_amdgcn_s_setprio(0); } while (0)
; #define PG8_WAIT_V(n) asm volatile("s_waitcnt vmcnt(" #n ")" ::: "memory")
; #define PG8_WAIT_L(n) asm volatile("s_waitcnt lgkmcnt(" #n ")" ::: "memory")
; #define PG8_BAR __builtin_amdgcn_s_barrier()
; #define PG8_SCHED __builtin_amdgcn_sched_barrier(0)
; template <class Epi, class Sched, bool ALIGN_EPI = false, bool SP2 = false>
; __device__ __forceinline__ void gemm_phase(PG8_LAS unsigned char* lds, const Gemm g, const Sched& S, const Epi& E) {
;     ...
;             PG8_WAIT_V(8); PG8_WAIT_L(0); PG8_BAR; PG8_MMA(1, 0, At, B0); PG8_MMA(1, 1, At, B1); PG8_BAR; PG8_SCHED;
;             PG8_LDB(B0, 1, 0); PG8_LDB(B1, 1, 1); PG8_SCHED; PG8_LDA(At, 1, 0); PG8_STAGE(PG8_SA(0, 1), a2 + hstep, voffA);
;             PG8_WAIT_V(8); PG8_WAIT_L(0); PG8_BAR; PG8_MMA(0, 0, At, B0); PG8_MMA(0, 1, At, B1); PG8_BAR; PG8_SCHED;
	v_mfma_f32_16x16x32_bf16 v[60:63], v[128:131], v[170:173], v[60:63]
	v_mfma_f32_16x16x32_bf16 v[56:59], v[136:139], v[170:173], v[56:59]
	v_mfma_f32_16x16x32_bf16 v[44:47], v[128:131], v[178:181], v[44:47]
	v_mfma_f32_16x16x32_bf16 v[40:43], v[136:139], v[178:181], v[40:43]
	v_mfma_f32_16x16x32_bf16 v[28:31], v[128:131], v[194:197], v[28:31]
	v_mfma_f32_16x16x32_bf16 v[24:27], v[136:139], v[194:197], v[24:27]
	v_mfma_f32_16x16x32_bf16 v[12:15], v[128:131], v[202:205], v[12:15]
	v_mfma_f32_16x16x32_bf16 v[8:11], v[136:139], v[202:205], v[8:11]
	v_mfma_f32_16x16x32_bf16 v[60:63], v[132:135], v[174:177], v[60:63]
	v_mfma_f32_16x16x32_bf16 v[56:59], v[140:143], v[174:177], v[56:59]
	v_mfma_f32_16x16x32_bf16 v[44:47], v[132:135], v[186:189], v[44:47]
	v_mfma_f32_16x16x32_bf16 v[40:43], v[140:143], v[186:189], v[40:43]
	v_mfma_f32_16x16x32_bf16 v[28:31], v[132:135], v[198:201], v[28:31]
	v_mfma_f32_16x16x32_bf16 v[24:27], v[140:143], v[198:201], v[24:27]
	v_mfma_f32_16x16x32_bf16 v[12:15], v[132:135], v[206:209], v[12:15]
	v_mfma_f32_16x16x32_bf16 v[8:11], v[140:143], v[206:209], v[8:11]
	s_setprio 0
	s_setprio 1
	v_mfma_f32_16x16x32_bf16 v[52:55], v[144:147], v[170:173], v[52:55]
	v_mfma_f32_16x16x32_bf16 v[48:51], v[152:155], v[170:173], v[48:51]
	v_mfma_f32_16x16x32_bf16 v[36:39], v[144:147], v[178:181], v[36:39]
	v_mfma_f32_16x16x32_bf16 v[32:35], v[152:155], v[178:181], v[32:35]
	v_mfma_f32_16x16x32_bf16 v[20:23], v[144:147], v[194:197], v[20:23]
	v_mfma_f32_16x16x32_bf16 v[16:19], v[152:155], v[194:197], v[16:19]
	v_mfma_f32_16x16x32_bf16 v[4:7], v[144:147], v[202:205], v[4:7]
	v_mfma_f32_16x16x32_bf16 v[0:3], v[152:155], v[202:205], v[0:3]
	v_mfma_f32_16x16x32_bf16 v[52:55], v[148:151], v[174:177], v[52:55]
	v_mfma_f32_16x16x32_bf16 v[48:51], v[166:169], v[174:177], v[48:51]
	v_mfma_f32_16x16x32_bf16 v[36:39], v[148:151], v[186:189], v[36:39]
	v_mfma_f32_16x16x32_bf16 v[32:35], v[166:169], v[186:189], v[32:35]
	v_mfma_f32_16x16x32_bf16 v[20:23], v[148:151], v[198:201], v[20:23]
	v_mfma_f32_16x16x32_bf16 v[16:19], v[166:169], v[198:201], v[16:19]
	v_mfma_f32_16x16x32_bf16 v[4:7], v[148:151], v[206:209], v[4:7]
	v_mfma_f32_16x16x32_bf16 v[0:3], v[166:169], v[206:209], v[0:3]
	s_barrier
	s_setprio 0
	s_add_i32 s10, 0, 0x18000
	s_add_i32 s11, 0, 0x1c000
	v_add_u32_e32 v140, s10, v183
	v_add_u32_e32 v166, s11, v183
	ds_read_b128 v[128:131], v140
	ds_read_b128 v[132:135], v140 offset:1024
	ds_read_b128 v[136:139], v140 offset:2048
	ds_read_b128 v[140:143], v140 offset:3072
	ds_read_b128 v[144:147], v166
	ds_read_b128 v[148:151], v166 offset:1024
	ds_read_b128 v[152:155], v166 offset:2048
	ds_read_b128 v[166:169], v166 offset:3072
	s_add_u32 s46, s46, s52
	s_addc_u32 s47, s47, 0
	s_mov_b32 m0, s68
	v_lshl_add_u64 v[220:221], s[46:47], 0, v[156:157]
	ds_read_b128 v[170:173], v185 offset:32768
	ds_read_b128 v[174:177], v185 offset:33792
	ds_read_b128 v[178:181], v185 offset:34816
	ds_read_b128 v[186:189], v185 offset:35840
	ds_read_b128 v[194:197], v185 offset:36864
	ds_read_b128 v[198:201], v185 offset:37888
	ds_read_b128 v[202:205], v185 offset:38912
	ds_read_b128 v[206:209], v185 offset:39936
	global_load_lds_dwordx4 v[220:221], off
	v_lshl_add_u64 v[220:221], s[46:47], 0, v[158:159]
	s_mov_b32 m0, s69
	s_nop 0
	global_load_lds_dwordx4 v[220:221], off
	s_waitcnt vmcnt(8)
	s_waitcnt lgkmcnt(0)
	s_setprio 1
	s_barrier
	v_mfma_f32_16x16x32_bf16 v[124:127], v[128:131], v[170:173], v[124:127]
	v_mfma_f32_16x16x32_bf16 v[120:123], v[136:139], v[170:173], v[120:123]
	v_mfma_f32_16x16x32_bf16 v[108:111], v[128:131], v[178:181], v[108:111]
	v_mfma_f32_16x16x32_bf16 v[104:107], v[136:139], v[178:181], v[104:107]
	v_mfma_f32_16x16x32_bf16 v[92:95], v[128:131], v[194:197], v[92:95]
	v_mfma_f32_16x16x32_bf16 v[88:91], v[136:139], v[194:197], v[88:91]
	v_mfma_f32_16x16x32_bf16 v[76:79], v[128:131], v[202:205], v[76:79]
	v_mfma_f32_16x16x32_bf16 v[72:75], v[136:139], v[202:205], v[72:75]
	v_mfma_f32_16x16x32_bf16 v[124:127], v[132:135], v[174:177], v[124:127]
	v_mfma_f32_16x16x32_bf16 v[120:123], v[140:143], v[174:177], v[120:123]
	v_mfma_f32_16x16x32_bf16 v[108:111], v[132:135], v[186:189], v[108:111]
	v_mfma_f32_16x16x32_bf16 v[104:107], v[140:143], v[186:189], v[104:107]
	v_mfma_f32_16x16x32_bf16 v[92:95], v[132:135], v[198:201], v[92:95]
	v_mfma_f32_16x16x32_bf16 v[88:91], v[140:143], v[198:201], v[88:91]
	v_mfma_f32_16x16x32_bf16 v[76:79], v[132:135], v[206:209], v[76:79]
	v_mfma_f32_16x16x32_bf16 v[72:75], v[140:143], v[206:209], v[72:75]
	s_setprio 0
	s_setprio 1
	v_mfma_f32_16x16x32_bf16 v[116:119], v[144:147], v[170:173], v[116:119]
	v_mfma_f32_16x16x32_bf16 v[112:115], v[152:155], v[170:173], v[112:115]
	v_mfma_f32_16x16x32_bf16 v[100:103], v[144:147], v[178:181], v[100:103]
	v_mfma_f32_16x16x32_bf16 v[96:99], v[152:155], v[178:181], v[96:99]
	v_mfma_f32_16x16x32_bf16 v[84:87], v[144:147], v[194:197], v[84:87]
	v_mfma_f32_16x16x32_bf16 v[80:83], v[152:155], v[194:197], v[80:83]
	v_mfma_f32_16x16x32_bf16 v[68:71], v[144:147], v[202:205], v[68:71]
	v_mfma_f32_16x16x32_bf16 v[64:67], v[152:155], v[202:205], v[64:67]
	v_mfma_f32_16x16x32_bf16 v[116:119], v[148:151], v[174:177], v[116:119]
	v_mfma_f32_16x16x32_bf16 v[112:115], v[166:169], v[174:177], v[112:115]
	v_mfma_f32_16x16x32_bf16 v[100:103], v[148:151], v[186:189], v[100:103]
	v_mfma_f32_16x16x32_bf16 v[96:99], v[166:169], v[186:189], v[96:99]
	v_mfma_f32_16x16x32_bf16 v[84:87], v[148:151], v[198:201], v[84:87]
	v_mfma_f32_16x16x32_bf16 v[80:83], v[166:169], v[198:201], v[80:83]
	v_mfma_f32_16x16x32_bf16 v[68:71], v[148:151], v[206:209], v[68:71]
	v_mfma_f32_16x16x32_bf16 v[64:67], v[166:169], v[206:209], v[64:67]
	s_barrier
; #define PG8_STAGE(bufoff, gbase, voff) do { _Pragma("unroll") for (int _i = 0; _i < 2; ++_i) \
;         __builtin_amdgcn_global_load_lds((const unsigned*)((const char*)(gbase) + (voff)[_i]), (PG8_LAS unsigned*)(lds + (bufoff) + ldsw + _i * 8192), 16, 0, 0); } while (0)
; #define PG8_LDA(dst, b, h) do { _Pragma("unroll") for (int m = 0; m < 4; ++m) _Pragma("unroll") for (int k = 0; k < 2; ++k) dst[m][k] = *(const PG8_LAS bf16x8*)(lds + PG8_SA(b, h) + aoff + m * 2048 + k * 1024); } while (0)
; #define PG8_MMA(ai, bj, At, Bt) do { __builtin_amdgcn_s_setprio(1); _Pragma("unroll") for (int m = 0; m < 4; ++m) _Pragma("unroll") for (int n = 0; n < 2; ++n) _Pragma("unroll") for (int k = 0; k < 2; ++k) \
;         acc[ai][bj][m][n] = __builtin_amdgcn_mfma_f32_16x16x32_bf16(Bt[n][k], At[m][k], acc[ai][bj][m][n], 0, 0, 0); __builtin_amdgcn_s_setprio(0); } while (0)
; #define PG8_WAIT_V(n) asm volatile("s_waitcnt vmcnt(" #n ")" ::: "memory")
; #define PG8_WAIT_L(n) asm volatile("s_waitcnt lgkmcnt(" #n ")" ::: "memory")
; #define PG8_BAR __builtin_amdgcn_s_barrier()
; #define PG8_SCHED __builtin_amdgcn_sched_barrier(0)
; template <class Epi, class Sched, bool ALIGN_EPI = false, bool SP2 = false>
; __device__ __forceinline__ void gemm_phase(PG8_LAS unsigned char* lds, const Gemm g, const Sched& S, const Epi& E) {
;     ...
;             PG8_LDA(At, 1, 1); PG8_STAGE(PG8_SB(1, 0), b3, voffB); PG8_STAGE(PG8_SB(1, 1), b3 + hstep, voffB); PG8_STAGE(PG8_SA(1, 0), a3, voffA);
;             PG8_WAIT_V(8); PG8_WAIT_L(0); PG8_BAR; PG8_MMA(1, 0, At, B0); PG8_MMA(1, 1, At, B1); PG8_BAR; PG8_SCHED;
;     ...
;         if constexpr (ALIGN_EPI) { if (wr == 0) PG8_BAR; }
	s_setprio 0
	s_add_i32 s10, s10, s22
	v_lshl_add_u64 v[190:191], v[190:191], 0, s[36:37]
	s_mov_b32 m0, s10
	ds_read_b128 v[170:173], v185 offset:49152
	ds_read_b128 v[174:177], v185 offset:50176
	ds_read_b128 v[178:181], v185 offset:51200
	ds_read_b128 v[186:189], v185 offset:52224
	ds_read_b128 v[194:197], v185 offset:53248
	ds_read_b128 v[198:201], v185 offset:54272
	ds_read_b128 v[202:205], v185 offset:55296
	ds_read_b128 v[206:209], v185 offset:56320
	global_load_lds_dwordx4 v[190:191], off
	v_lshl_add_u64 v[190:191], v[210:211], 0, s[36:37]
	s_add_i32 m0, s10, 0x2000
	s_add_i32 s10, s11, s22
	global_load_lds_dwordx4 v[190:191], off
	v_lshl_add_u64 v[190:191], v[212:213], 0, s[36:37]
	s_mov_b32 m0, s10
	s_nop 0
	global_load_lds_dwordx4 v[190:191], off
	v_lshl_add_u64 v[190:191], v[214:215], 0, s[36:37]
	s_add_i32 m0, s10, 0x2000
	s_nop 0
	global_load_lds_dwordx4 v[190:191], off
	v_lshl_add_u64 v[190:191], v[216:217], 0, s[36:37]
	s_mov_b32 m0, s70
	s_nop 0
	global_load_lds_dwordx4 v[190:191], off
	v_lshl_add_u64 v[190:191], v[218:219], 0, s[36:37]
	s_mov_b32 m0, s71
	s_nop 0
	global_load_lds_dwordx4 v[190:191], off
	s_waitcnt vmcnt(8)
	s_waitcnt lgkmcnt(0)
	s_setprio 1
	s_barrier
	v_mfma_f32_16x16x32_bf16 v[60:63], v[128:131], v[170:173], v[60:63]
	v_mfma_f32_16x16x32_bf16 v[56:59], v[136:139], v[170:173], v[56:59]
	v_mfma_f32_16x16x32_bf16 v[44:47], v[128:131], v[178:181], v[44:47]
	v_mfma_f32_16x16x32_bf16 v[40:43], v[136:139], v[178:181], v[40:43]
	v_mfma_f32_16x16x32_bf16 v[28:31], v[128:131], v[194:197], v[28:31]
	v_mfma_f32_16x16x32_bf16 v[24:27], v[136:139], v[194:197], v[24:27]
	v_mfma_f32_16x16x32_bf16 v[12:15], v[128:131], v[202:205], v[12:15]
	v_mfma_f32_16x16x32_bf16 v[8:11], v[136:139], v[202:205], v[8:11]
	v_mfma_f32_16x16x32_bf16 v[60:63], v[132:135], v[174:177], v[60:63]
	v_mfma_f32_16x16x32_bf16 v[56:59], v[140:143], v[174:177], v[56:59]
	v_mfma_f32_16x16x32_bf16 v[44:47], v[132:135], v[186:189], v[44:47]
	v_mfma_f32_16x16x32_bf16 v[40:43], v[140:143], v[186:189], v[40:43]
	v_mfma_f32_16x16x32_bf16 v[28:31], v[132:135], v[198:201], v[28:31]
	v_mfma_f32_16x16x32_bf16 v[24:27], v[140:143], v[198:201], v[24:27]
	v_mfma_f32_16x16x32_bf16 v[12:15], v[132:135], v[206:209], v[12:15]
	v_mfma_f32_16x16x32_bf16 v[8:11], v[140:143], v[206:209], v[8:11]
	s_setprio 0
	s_setprio 1
	v_mfma_f32_16x16x32_bf16 v[52:55], v[144:147], v[170:173], v[52:55]
	v_mfma_f32_16x16x32_bf16 v[48:51], v[152:155], v[170:173], v[48:51]
	v_mfma_f32_16x16x32_bf16 v[36:39], v[144:147], v[178:181], v[36:39]
	v_mfma_f32_16x16x32_bf16 v[32:35], v[152:155], v[178:181], v[32:35]
	v_mfma_f32_16x16x32_bf16 v[20:23], v[144:147], v[194:197], v[20:23]
	v_mfma_f32_16x16x32_bf16 v[16:19], v[152:155], v[194:197], v[16:19]
	v_mfma_f32_16x16x32_bf16 v[4:7], v[144:147], v[202:205], v[4:7]
	v_mfma_f32_16x16x32_bf16 v[0:3], v[152:155], v[202:205], v[0:3]
	v_mfma_f32_16x16x32_bf16 v[52:55], v[148:151], v[174:177], v[52:55]
	v_mfma_f32_16x16x32_bf16 v[48:51], v[166:169], v[174:177], v[48:51]
	v_mfma_f32_16x16x32_bf16 v[36:39], v[148:151], v[186:189], v[36:39]
	v_mfma_f32_16x16x32_bf16 v[32:35], v[166:169], v[186:189], v[32:35]
	v_mfma_f32_16x16x32_bf16 v[20:23], v[148:151], v[198:201], v[20:23]
	v_mfma_f32_16x16x32_bf16 v[16:19], v[166:169], v[198:201], v[16:19]
	v_mfma_f32_16x16x32_bf16 v[4:7], v[148:151], v[206:209], v[4:7]
	v_mfma_f32_16x16x32_bf16 v[0:3], v[166:169], v[206:209], v[0:3]
	s_cbranch_vccnz .Llast2_g1
	s_barrier
	s_setprio 0
	s_add_u32 s44, s44, 0x100
	s_addc_u32 s45, s45, 0
	s_add_u32 s19, s19, 0x100
	s_addc_u32 s20, s20, 0
	s_cmp_ge_u32 s66, s73
	s_mov_b32 s46, s66
	s_branch .LBB0_63
.Llast2_g1:
	s_setprio 0
	s_add_u32 s44, s44, 0x100
	s_addc_u32 s45, s45, 0
	s_add_u32 s19, s19, 0x100
	s_addc_u32 s20, s20, 0
	s_cmp_ge_u32 s66, s73
	s_mov_b32 s46, s66
	s_and_b64 vcc, exec, s[56:57]
	s_cbranch_vccz .LBB0_66
	s_barrier

; #define PG8_STAGE(bufoff, gbase, voff) do { _Pragma("unroll") for (int _i = 0; _i < 2; ++_i) \
;         __builtin_amdgcn_global_load_lds((const unsigned*)((const char*)(gbase) + (voff)[_i]), (PG8_LAS unsigned*)(lds + (bufoff) + ldsw + _i * 8192), 16, 0, 0); } while (0)
; #define PG8_LDA(dst, b, h) do { _Pragma("unroll") for (int m = 0; m < 4; ++m) _Pragma("unroll") for (int k = 0; k < 2; ++k) dst[m][k] = *(const PG8_LAS bf16x8*)(lds + PG8_SA(b, h) + aoff + m * 2048 + k * 1024); } while (0)
; #define PG8_LDB(dst, b, h) do { _Pragma("unroll") for (int n = 0; n < 2; ++n) _Pragma("unroll") for (int k = 0; k < 2; ++k) dst[n][k] = *(const PG8_LAS bf16x8*)(lds + PG8_SB(b, h) + boff + n * 2048 + k * 1024); } while (0)
; #define PG8_MMA(ai, bj, At, Bt) do { __builtin_amdgcn_s_setprio(1); _Pragma("unroll") for (int m = 0; m < 4; ++m) _Pragma("unroll") for (int n = 0; n < 2; ++n) _Pragma("unroll") for (int k = 0; k < 2; ++k) \
;         acc[ai][bj][m][n] = __builtin_amdgcn_mfma_f32_16x16x32_bf16(Bt[n][k], At[m][k], acc[ai][bj][m][n], 0, 0, 0); __builtin_amdgcn_s_setprio(0); } while (0)
; #define PG8_WAIT_V(n) asm volatile("s_waitcnt vmcnt(" #n ")" ::: "memory")
; #define PG8_WAIT_L(n) asm volatile("s_waitcnt lgkmcnt(" #n ")" ::: "memory")
; template <class Epi, class Sched, bool ALIGN_EPI = false, bool SP2 = false>
; __device__ __forceinline__ void gemm_phase(PG8_LAS unsigned char* lds, const Gemm g, const Sched& S, const Epi& E) {
;     ...
;             const bool last = (t == nt - 2);
;             const char* a1 = cA + (size_t)(t + 1) * kstep;
;             const char* a2 = last ? nA : cA + (size_t)(t + 2) * kstep; const char* b2 = last ? nB : cB + (size_t)(t + 2) * kstep;
;             const char* a3 = a2 + kstep; const char* b3 = b2 + kstep;
;             if (last && has_next) S.a_ready(nxt);
;             if constexpr (SP2) {
;             PG8_LDB(B0, 0, 0); PG8_LDB(B1, 0, 1); PG8_SCHED; PG8_LDA(At, 0, 0); PG8_STAGE(PG8_SA(1, 1), a1 + hstep, voffA);
;             PG8_WAIT_V(8); PG8_WAIT_L(0); PG8_BAR; PG8_MMA(0, 0, At, B0); PG8_MMA(0, 1, At, B1); PG8_BAR; PG8_SCHED;
;             PG8_LDA(At, 0, 1); PG8_STAGE(PG8_SB(0, 0), b2, voffB); PG8_STAGE(PG8_SB(0, 1), b2 + hstep, voffB); PG8_STAGE(PG8_SA(0, 0), a2, voffA);
;             PG8_WAIT_V(8); PG8_WAIT_L(0); PG8_BAR; PG8_MMA(1, 0, At, B0); PG8_MMA(1, 1, At, B1); PG8_BAR; PG8_SCHED;
.LBB0_200:
	s_add_u32 s10, s56, 0xfffc0080
	s_addc_u32 s11, s57, -1
	s_add_i32 s77, 0, 0x10000
	s_cmp_eq_u32 s76, 12
	s_cselect_b64 vcc, -1, 0
	s_cselect_b32 s61, s18, s11
	s_cselect_b32 s60, s19, s10
	s_cselect_b32 s59, s20, s51
	s_cselect_b32 s58, s43, s49
	s_add_i32 s10, 0, 0x14000
	v_add_u32_e32 v140, s77, v163
	v_add_u32_e32 v162, s10, v163
	ds_read_b128 v[128:131], v140
	ds_read_b128 v[132:135], v140 offset:1024
	ds_read_b128 v[136:139], v140 offset:2048
	ds_read_b128 v[140:143], v140 offset:3072
	ds_read_b128 v[166:169], v162
	ds_read_b128 v[170:173], v162 offset:1024
	ds_read_b128 v[174:177], v162 offset:2048
	ds_read_b128 v[178:181], v162 offset:3072
	v_lshl_add_u64 v[190:191], s[56:57], 0, v[158:159]
	s_add_i32 m0, s64, 0xc000
	ds_read_b128 v[182:185], v165
	ds_read_b128 v[186:189], v165 offset:1024
	ds_read_b128 v[194:197], v165 offset:2048
	ds_read_b128 v[198:201], v165 offset:3072
	ds_read_b128 v[202:205], v165 offset:4096
	ds_read_b128 v[206:209], v165 offset:5120
	ds_read_b128 v[210:213], v165 offset:6144
	ds_read_b128 v[214:217], v165 offset:7168
	global_load_lds_dwordx4 v[190:191], off
	v_lshl_add_u64 v[190:191], s[56:57], 0, v[160:161]
	s_add_i32 m0, s64, 0xe000
	s_nop 0
	global_load_lds_dwordx4 v[190:191], off
	s_waitcnt vmcnt(8)
	s_waitcnt lgkmcnt(0)
	s_setprio 1
	s_barrier
	v_mfma_f32_16x16x32_bf16 v[124:127], v[128:131], v[182:185], v[124:127]
	v_mfma_f32_16x16x32_bf16 v[120:123], v[136:139], v[182:185], v[120:123]
	v_mfma_f32_16x16x32_bf16 v[112:115], v[128:131], v[194:197], v[112:115]
	v_mfma_f32_16x16x32_bf16 v[104:107], v[136:139], v[194:197], v[104:107]
	v_mfma_f32_16x16x32_bf16 v[96:99], v[128:131], v[202:205], v[96:99]
	v_mfma_f32_16x16x32_bf16 v[88:91], v[136:139], v[202:205], v[88:91]
	v_mfma_f32_16x16x32_bf16 v[80:83], v[128:131], v[210:213], v[80:83]
	v_mfma_f32_16x16x32_bf16 v[72:75], v[136:139], v[210:213], v[72:75]
	v_mfma_f32_16x16x32_bf16 v[124:127], v[132:135], v[186:189], v[124:127]
	v_mfma_f32_16x16x32_bf16 v[120:123], v[140:143], v[186:189], v[120:123]
	v_mfma_f32_16x16x32_bf16 v[112:115], v[132:135], v[198:201], v[112:115]
	v_mfma_f32_16x16x32_bf16 v[104:107], v[140:143], v[198:201], v[104:107]
	v_mfma_f32_16x16x32_bf16 v[96:99], v[132:135], v[206:209], v[96:99]
	v_mfma_f32_16x16x32_bf16 v[88:91], v[140:143], v[206:209], v[88:91]
	v_mfma_f32_16x16x32_bf16 v[80:83], v[132:135], v[214:217], v[80:83]
	v_mfma_f32_16x16x32_bf16 v[72:75], v[140:143], v[214:217], v[72:75]
	s_setprio 0
	s_setprio 1
	v_mfma_f32_16x16x32_bf16 v[116:119], v[166:169], v[182:185], v[116:119]
	v_mfma_f32_16x16x32_bf16 v[108:111], v[174:177], v[182:185], v[108:111]
	v_mfma_f32_16x16x32_bf16 v[100:103], v[166:169], v[194:197], v[100:103]
	v_mfma_f32_16x16x32_bf16 v[92:95], v[174:177], v[194:197], v[92:95]
	v_mfma_f32_16x16x32_bf16 v[84:87], v[166:169], v[202:205], v[84:87]
	v_mfma_f32_16x16x32_bf16 v[76:79], v[174:177], v[202:205], v[76:79]
	v_mfma_f32_16x16x32_bf16 v[68:71], v[166:169], v[210:213], v[68:71]
	v_mfma_f32_16x16x32_bf16 v[64:67], v[174:177], v[210:213], v[64:67]
	v_mfma_f32_16x16x32_bf16 v[116:119], v[170:173], v[186:189], v[116:119]
	v_mfma_f32_16x16x32_bf16 v[108:111], v[178:181], v[186:189], v[108:111]
	v_mfma_f32_16x16x32_bf16 v[100:103], v[170:173], v[198:201], v[100:103]
	v_mfma_f32_16x16x32_bf16 v[92:95], v[178:181], v[198:201], v[92:95]
	v_mfma_f32_16x16x32_bf16 v[84:87], v[170:173], v[206:209], v[84:87]
	v_mfma_f32_16x16x32_bf16 v[76:79], v[178:181], v[206:209], v[76:79]
	v_mfma_f32_16x16x32_bf16 v[68:71], v[170:173], v[214:217], v[68:71]
	v_mfma_f32_16x16x32_bf16 v[64:67], v[178:181], v[214:217], v[64:67]
	s_barrier
	s_setprio 0
	s_add_i32 s11, s77, s63
	v_lshl_add_u64 v[190:191], s[58:59], 0, v[146:147]
	s_mov_b32 m0, s11
	ds_read_b128 v[182:185], v165 offset:16384
	ds_read_b128 v[186:189], v165 offset:17408
	ds_read_b128 v[194:197], v165 offset:18432
	ds_read_b128 v[198:201], v165 offset:19456
	ds_read_b128 v[202:205], v165 offset:20480
	ds_read_b128 v[206:209], v165 offset:21504
	ds_read_b128 v[210:213], v165 offset:22528
	ds_read_b128 v[214:217], v165 offset:23552
	global_load_lds_dwordx4 v[190:191], off
	s_add_i32 m0, s11, 0x2000
	s_add_u32 s78, s58, 0x40000
	v_lshl_add_u64 v[218:219], s[58:59], 0, v[150:151]
	s_addc_u32 s79, s59, 0
	s_add_i32 s10, s10, s63
	global_load_lds_dwordx4 v[218:219], off
	v_lshl_add_u64 v[220:221], s[78:79], 0, v[146:147]
	s_mov_b32 m0, s10
	v_lshl_add_u64 v[222:223], s[60:61], 0, v[148:149]
	global_load_lds_dwordx4 v[220:221], off
	v_lshl_add_u64 v[220:221], s[78:79], 0, v[150:151]
	s_add_i32 m0, s10, 0x2000
	s_nop 0
	global_load_lds_dwordx4 v[220:221], off
	v_lshl_add_u64 v[220:221], s[60:61], 0, v[144:145]
	s_mov_b32 m0, s64
	s_nop 0
	global_load_lds_dwordx4 v[220:221], off
	s_mov_b32 m0, s65
	s_nop 0
	global_load_lds_dwordx4 v[222:223], off
	s_waitcnt vmcnt(8)
	s_waitcnt lgkmcnt(0)
	s_setprio 1
	s_barrier
; #define PG8_STAGE(bufoff, gbase, voff) do { _Pragma("unroll") for (int _i = 0; _i < 2; ++_i) \
;         __builtin_amdgcn_global_load_lds((const unsigned*)((const char*)(gbase) + (voff)[_i]), (PG8_LAS unsigned*)(lds + (bufoff) + ldsw + _i * 8192), 16, 0, 0); } while (0)
; #define PG8_LDA(dst, b, h) do { _Pragma("unroll") for (int m = 0; m < 4; ++m) _Pragma("unroll") for (int k = 0; k < 2; ++k) dst[m][k] = *(const PG8_LAS bf16x8*)(lds + PG8_SA(b, h) + aoff + m * 2048 + k * 1024); } while (0)
; #define PG8_LDB(dst, b, h) do { _Pragma("unroll") for (int n = 0; n < 2; ++n) _Pragma("unroll") for (int k = 0; k < 2; ++k) dst[n][k] = *(const PG8_LAS bf16x8*)(lds + PG8_SB(b, h) + boff + n * 2048 + k * 1024); } while (0)
; #define PG8_MMA(ai, bj, At, Bt) do { __builtin_amdgcn_s_setprio(1); _Pragma("unroll") for (int m = 0; m < 4; ++m) _Pragma("unroll") for (int n = 0; n < 2; ++n) _Pragma("unroll") for (int k = 0; k < 2; ++k) \
;         acc[ai][bj][m][n] = __builtin_amdgcn_mfma_f32_16x16x32_bf16(Bt[n][k], At[m][k], acc[ai][bj][m][n], 0, 0, 0); __builtin_amdgcn_s_setprio(0); } while (0)
; #define PG8_WAIT_V(n) asm volatile("s_waitcnt vmcnt(" #n ")" ::: "memory")
; #define PG8_WAIT_L(n) asm volatile("s_waitcnt lgkmcnt(" #n ")" ::: "memory")
; #define PG8_BAR __builtin_amdgcn_s_barrier()
; #define PG8_SCHED __builtin_amdgcn_sched_barrier(0)
; template <class Epi, class Sched, bool ALIGN_EPI = false, bool SP2 = false>
; __device__ __forceinline__ void gemm_phase(PG8_LAS unsigned char* lds, const Gemm g, const Sched& S, const Epi& E) {
;     ...
;             PG8_WAIT_V(8); PG8_WAIT_L(0); PG8_BAR; PG8_MMA(1, 0, At, B0); PG8_MMA(1, 1, At, B1); PG8_BAR; PG8_SCHED;
;             PG8_LDB(B0, 1, 0); PG8_LDB(B1, 1, 1); PG8_SCHED; PG8_LDA(At, 1, 0); PG8_STAGE(PG8_SA(0, 1), a2 + hstep, voffA);
;             PG8_WAIT_V(8); PG8_WAIT_L(0); PG8_BAR; PG8_MMA(0, 0, At, B0); PG8_MMA(0, 1, At, B1); PG8_BAR; PG8_SCHED;
	v_mfma_f32_16x16x32_bf16 v[60:63], v[128:131], v[182:185], v[60:63]
	v_mfma_f32_16x16x32_bf16 v[56:59], v[136:139], v[182:185], v[56:59]
	v_mfma_f32_16x16x32_bf16 v[48:51], v[128:131], v[194:197], v[48:51]
	v_mfma_f32_16x16x32_bf16 v[40:43], v[136:139], v[194:197], v[40:43]
	v_mfma_f32_16x16x32_bf16 v[32:35], v[128:131], v[202:205], v[32:35]
	v_mfma_f32_16x16x32_bf16 v[24:27], v[136:139], v[202:205], v[24:27]
	v_mfma_f32_16x16x32_bf16 v[16:19], v[128:131], v[210:213], v[16:19]
	v_mfma_f32_16x16x32_bf16 v[8:11], v[136:139], v[210:213], v[8:11]
	v_mfma_f32_16x16x32_bf16 v[60:63], v[132:135], v[186:189], v[60:63]
	v_mfma_f32_16x16x32_bf16 v[56:59], v[140:143], v[186:189], v[56:59]
	v_mfma_f32_16x16x32_bf16 v[48:51], v[132:135], v[198:201], v[48:51]
	v_mfma_f32_16x16x32_bf16 v[40:43], v[140:143], v[198:201], v[40:43]
	v_mfma_f32_16x16x32_bf16 v[32:35], v[132:135], v[206:209], v[32:35]
	v_mfma_f32_16x16x32_bf16 v[24:27], v[140:143], v[206:209], v[24:27]
	v_mfma_f32_16x16x32_bf16 v[16:19], v[132:135], v[214:217], v[16:19]
	v_mfma_f32_16x16x32_bf16 v[8:11], v[140:143], v[214:217], v[8:11]
	s_setprio 0
	s_setprio 1
	v_mfma_f32_16x16x32_bf16 v[52:55], v[166:169], v[182:185], v[52:55]
	v_mfma_f32_16x16x32_bf16 v[44:47], v[174:177], v[182:185], v[44:47]
	v_mfma_f32_16x16x32_bf16 v[36:39], v[166:169], v[194:197], v[36:39]
	v_mfma_f32_16x16x32_bf16 v[28:31], v[174:177], v[194:197], v[28:31]
	v_mfma_f32_16x16x32_bf16 v[20:23], v[166:169], v[202:205], v[20:23]
	v_mfma_f32_16x16x32_bf16 v[12:15], v[174:177], v[202:205], v[12:15]
	v_mfma_f32_16x16x32_bf16 v[4:7], v[166:169], v[210:213], v[4:7]
	v_mfma_f32_16x16x32_bf16 v[0:3], v[174:177], v[210:213], v[0:3]
	v_mfma_f32_16x16x32_bf16 v[52:55], v[170:173], v[186:189], v[52:55]
	v_mfma_f32_16x16x32_bf16 v[44:47], v[178:181], v[186:189], v[44:47]
	v_mfma_f32_16x16x32_bf16 v[36:39], v[170:173], v[198:201], v[36:39]
	v_mfma_f32_16x16x32_bf16 v[28:31], v[178:181], v[198:201], v[28:31]
	v_mfma_f32_16x16x32_bf16 v[20:23], v[170:173], v[206:209], v[20:23]
	v_mfma_f32_16x16x32_bf16 v[12:15], v[178:181], v[206:209], v[12:15]
	v_mfma_f32_16x16x32_bf16 v[4:7], v[170:173], v[214:217], v[4:7]
	v_mfma_f32_16x16x32_bf16 v[0:3], v[178:181], v[214:217], v[0:3]
	s_barrier
	s_setprio 0
	s_add_i32 s10, 0, 0x18000
	s_add_i32 s11, 0, 0x1c000
	v_add_u32_e32 v140, s10, v163
	v_add_u32_e32 v162, s11, v163
	ds_read_b128 v[128:131], v140
	ds_read_b128 v[132:135], v140 offset:1024
	ds_read_b128 v[136:139], v140 offset:2048
	ds_read_b128 v[140:143], v140 offset:3072
	ds_read_b128 v[166:169], v162
	ds_read_b128 v[170:173], v162 offset:1024
	ds_read_b128 v[174:177], v162 offset:2048
	ds_read_b128 v[178:181], v162 offset:3072
	s_add_u32 s60, s60, 0x40000
	s_addc_u32 s61, s61, 0
	s_mov_b32 m0, s66
	v_lshl_add_u64 v[224:225], s[60:61], 0, v[144:145]
	ds_read_b128 v[182:185], v165 offset:32768
	ds_read_b128 v[186:189], v165 offset:33792
	ds_read_b128 v[194:197], v165 offset:34816
	ds_read_b128 v[198:201], v165 offset:35840
	ds_read_b128 v[202:205], v165 offset:36864
	ds_read_b128 v[206:209], v165 offset:37888
	ds_read_b128 v[210:213], v165 offset:38912
	ds_read_b128 v[214:217], v165 offset:39936
	global_load_lds_dwordx4 v[224:225], off
	v_lshl_add_u64 v[224:225], s[60:61], 0, v[148:149]
	s_mov_b32 m0, s67
	s_nop 0
	global_load_lds_dwordx4 v[224:225], off
	s_waitcnt vmcnt(8)
	s_waitcnt lgkmcnt(0)
	s_setprio 1
	s_barrier
	v_mfma_f32_16x16x32_bf16 v[124:127], v[128:131], v[182:185], v[124:127]
	v_mfma_f32_16x16x32_bf16 v[120:123], v[136:139], v[182:185], v[120:123]
	v_mfma_f32_16x16x32_bf16 v[112:115], v[128:131], v[194:197], v[112:115]
	v_mfma_f32_16x16x32_bf16 v[104:107], v[136:139], v[194:197], v[104:107]
	v_mfma_f32_16x16x32_bf16 v[96:99], v[128:131], v[202:205], v[96:99]
	v_mfma_f32_16x16x32_bf16 v[88:91], v[136:139], v[202:205], v[88:91]
	v_mfma_f32_16x16x32_bf16 v[80:83], v[128:131], v[210:213], v[80:83]
	v_mfma_f32_16x16x32_bf16 v[72:75], v[136:139], v[210:213], v[72:75]
	v_mfma_f32_16x16x32_bf16 v[124:127], v[132:135], v[186:189], v[124:127]
	v_mfma_f32_16x16x32_bf16 v[120:123], v[140:143], v[186:189], v[120:123]
	v_mfma_f32_16x16x32_bf16 v[112:115], v[132:135], v[198:201], v[112:115]
	v_mfma_f32_16x16x32_bf16 v[104:107], v[140:143], v[198:201], v[104:107]
	v_mfma_f32_16x16x32_bf16 v[96:99], v[132:135], v[206:209], v[96:99]
	v_mfma_f32_16x16x32_bf16 v[88:91], v[140:143], v[206:209], v[88:91]
	v_mfma_f32_16x16x32_bf16 v[80:83], v[132:135], v[214:217], v[80:83]
	v_mfma_f32_16x16x32_bf16 v[72:75], v[140:143], v[214:217], v[72:75]
	s_setprio 0
	s_setprio 1
	v_mfma_f32_16x16x32_bf16 v[116:119], v[166:169], v[182:185], v[116:119]
	v_mfma_f32_16x16x32_bf16 v[108:111], v[174:177], v[182:185], v[108:111]
	v_mfma_f32_16x16x32_bf16 v[100:103], v[166:169], v[194:197], v[100:103]
	v_mfma_f32_16x16x32_bf16 v[92:95], v[174:177], v[194:197], v[92:95]
	v_mfma_f32_16x16x32_bf16 v[84:87], v[166:169], v[202:205], v[84:87]
	v_mfma_f32_16x16x32_bf16 v[76:79], v[174:177], v[202:205], v[76:79]
	v_mfma_f32_16x16x32_bf16 v[68:71], v[166:169], v[210:213], v[68:71]
	v_mfma_f32_16x16x32_bf16 v[64:67], v[174:177], v[210:213], v[64:67]
	v_mfma_f32_16x16x32_bf16 v[116:119], v[170:173], v[186:189], v[116:119]
	v_mfma_f32_16x16x32_bf16 v[108:111], v[178:181], v[186:189], v[108:111]
	v_mfma_f32_16x16x32_bf16 v[100:103], v[170:173], v[198:201], v[100:103]
	v_mfma_f32_16x16x32_bf16 v[92:95], v[178:181], v[198:201], v[92:95]
	v_mfma_f32_16x16x32_bf16 v[84:87], v[170:173], v[206:209], v[84:87]
	v_mfma_f32_16x16x32_bf16 v[76:79], v[178:181], v[206:209], v[76:79]
	v_mfma_f32_16x16x32_bf16 v[68:71], v[170:173], v[214:217], v[68:71]
	v_mfma_f32_16x16x32_bf16 v[64:67], v[178:181], v[214:217], v[64:67]
	s_barrier
; #define PG8_STAGE(bufoff, gbase, voff) do { _Pragma("unroll") for (int _i = 0; _i < 2; ++_i) \
;         __builtin_amdgcn_global_load_lds((const unsigned*)((const char*)(gbase) + (voff)[_i]), (PG8_LAS unsigned*)(lds + (bufoff) + ldsw + _i * 8192), 16, 0, 0); } while (0)
; #define PG8_LDA(dst, b, h) do { _Pragma("unroll") for (int m = 0; m < 4; ++m) _Pragma("unroll") for (int k = 0; k < 2; ++k) dst[m][k] = *(const PG8_LAS bf16x8*)(lds + PG8_SA(b, h) + aoff + m * 2048 + k * 1024); } while (0)
; #define PG8_MMA(ai, bj, At, Bt) do { __builtin_amdgcn_s_setprio(1); _Pragma("unroll") for (int m = 0; m < 4; ++m) _Pragma("unroll") for (int n = 0; n < 2; ++n) _Pragma("unroll") for (int k = 0; k < 2; ++k) \
;         acc[ai][bj][m][n] = __builtin_amdgcn_mfma_f32_16x16x32_bf16(Bt[n][k], At[m][k], acc[ai][bj][m][n], 0, 0, 0); __builtin_amdgcn_s_setprio(0); } while (0)
; #define PG8_WAIT_V(n) asm volatile("s_waitcnt vmcnt(" #n ")" ::: "memory")
; #define PG8_WAIT_L(n) asm volatile("s_waitcnt lgkmcnt(" #n ")" ::: "memory")
; #define PG8_BAR __builtin_amdgcn_s_barrier()
; #define PG8_SCHED __builtin_amdgcn_sched_barrier(0)
; template <class Epi, class Sched, bool ALIGN_EPI = false, bool SP2 = false>
; __device__ __forceinline__ void gemm_phase(PG8_LAS unsigned char* lds, const Gemm g, const Sched& S, const Epi& E) {
;     ...
;             PG8_LDA(At, 1, 1); PG8_STAGE(PG8_SB(1, 0), b3, voffB); PG8_STAGE(PG8_SB(1, 1), b3 + hstep, voffB); PG8_STAGE(PG8_SA(1, 0), a3, voffA);
;             PG8_WAIT_V(8); PG8_WAIT_L(0); PG8_BAR; PG8_MMA(1, 0, At, B0); PG8_MMA(1, 1, At, B1); PG8_BAR; PG8_SCHED;
;     ...
;         if constexpr (ALIGN_EPI) { if (wr == 0) PG8_BAR; }
	s_setprio 0
	s_add_i32 s10, s10, s63
	v_lshl_add_u64 v[190:191], v[190:191], 0, s[36:37]
	s_mov_b32 m0, s10
	ds_read_b128 v[182:185], v165 offset:49152
	ds_read_b128 v[186:189], v165 offset:50176
	ds_read_b128 v[194:197], v165 offset:51200
	ds_read_b128 v[198:201], v165 offset:52224
	ds_read_b128 v[202:205], v165 offset:53248
	ds_read_b128 v[206:209], v165 offset:54272
	ds_read_b128 v[210:213], v165 offset:55296
	ds_read_b128 v[214:217], v165 offset:56320
	global_load_lds_dwordx4 v[190:191], off
	s_add_i32 m0, s10, 0x2000
	s_add_u32 s58, s58, 0x40080
	v_lshl_add_u64 v[190:191], v[218:219], 0, s[36:37]
	s_addc_u32 s59, s59, 0
	s_add_i32 s10, s11, s63
	global_load_lds_dwordx4 v[190:191], off
	v_lshl_add_u64 v[190:191], s[58:59], 0, v[146:147]
	s_mov_b32 m0, s10
	s_nop 0
	global_load_lds_dwordx4 v[190:191], off
	v_lshl_add_u64 v[190:191], s[58:59], 0, v[150:151]
	s_add_i32 m0, s10, 0x2000
	s_nop 0
	global_load_lds_dwordx4 v[190:191], off
	v_lshl_add_u64 v[190:191], v[220:221], 0, s[36:37]
	s_mov_b32 m0, s70
	s_nop 0
	global_load_lds_dwordx4 v[190:191], off
	v_lshl_add_u64 v[190:191], v[222:223], 0, s[36:37]
	s_mov_b32 m0, s71
	s_nop 0
	global_load_lds_dwordx4 v[190:191], off
	s_waitcnt vmcnt(8)
	s_waitcnt lgkmcnt(0)
	s_setprio 1
	s_barrier
	v_mfma_f32_16x16x32_bf16 v[60:63], v[128:131], v[182:185], v[60:63]
	v_mfma_f32_16x16x32_bf16 v[56:59], v[136:139], v[182:185], v[56:59]
	v_mfma_f32_16x16x32_bf16 v[48:51], v[128:131], v[194:197], v[48:51]
	v_mfma_f32_16x16x32_bf16 v[40:43], v[136:139], v[194:197], v[40:43]
	v_mfma_f32_16x16x32_bf16 v[32:35], v[128:131], v[202:205], v[32:35]
	v_mfma_f32_16x16x32_bf16 v[24:27], v[136:139], v[202:205], v[24:27]
	v_mfma_f32_16x16x32_bf16 v[16:19], v[128:131], v[210:213], v[16:19]
	v_mfma_f32_16x16x32_bf16 v[8:11], v[136:139], v[210:213], v[8:11]
	v_mfma_f32_16x16x32_bf16 v[60:63], v[132:135], v[186:189], v[60:63]
	v_mfma_f32_16x16x32_bf16 v[56:59], v[140:143], v[186:189], v[56:59]
	v_mfma_f32_16x16x32_bf16 v[48:51], v[132:135], v[198:201], v[48:51]
	v_mfma_f32_16x16x32_bf16 v[40:43], v[140:143], v[198:201], v[40:43]
	v_mfma_f32_16x16x32_bf16 v[32:35], v[132:135], v[206:209], v[32:35]
	v_mfma_f32_16x16x32_bf16 v[24:27], v[140:143], v[206:209], v[24:27]
	v_mfma_f32_16x16x32_bf16 v[16:19], v[132:135], v[214:217], v[16:19]
	v_mfma_f32_16x16x32_bf16 v[8:11], v[140:143], v[214:217], v[8:11]
	s_setprio 0
	s_setprio 1
	v_mfma_f32_16x16x32_bf16 v[52:55], v[166:169], v[182:185], v[52:55]
	v_mfma_f32_16x16x32_bf16 v[44:47], v[174:177], v[182:185], v[44:47]
	v_mfma_f32_16x16x32_bf16 v[36:39], v[166:169], v[194:197], v[36:39]
	v_mfma_f32_16x16x32_bf16 v[28:31], v[174:177], v[194:197], v[28:31]
	v_mfma_f32_16x16x32_bf16 v[20:23], v[166:169], v[202:205], v[20:23]
	v_mfma_f32_16x16x32_bf16 v[12:15], v[174:177], v[202:205], v[12:15]
	v_mfma_f32_16x16x32_bf16 v[4:7], v[166:169], v[210:213], v[4:7]
	v_mfma_f32_16x16x32_bf16 v[0:3], v[174:177], v[210:213], v[0:3]
	v_mfma_f32_16x16x32_bf16 v[52:55], v[170:173], v[186:189], v[52:55]
	v_mfma_f32_16x16x32_bf16 v[44:47], v[178:181], v[186:189], v[44:47]
	v_mfma_f32_16x16x32_bf16 v[36:39], v[170:173], v[198:201], v[36:39]
	v_mfma_f32_16x16x32_bf16 v[28:31], v[178:181], v[198:201], v[28:31]
	v_mfma_f32_16x16x32_bf16 v[20:23], v[170:173], v[206:209], v[20:23]
	v_mfma_f32_16x16x32_bf16 v[12:15], v[178:181], v[206:209], v[12:15]
	v_mfma_f32_16x16x32_bf16 v[4:7], v[170:173], v[214:217], v[4:7]
	v_mfma_f32_16x16x32_bf16 v[0:3], v[178:181], v[214:217], v[0:3]
	s_cbranch_vccnz .Llast2_g2
	s_barrier
	s_setprio 0
	s_add_i32 s76, s76, 2
	s_add_u32 s56, s56, 0x100
	s_addc_u32 s57, s57, 0
	s_add_u32 s49, s49, 0x100
	s_addc_u32 s51, s51, 0
	s_cmp_gt_u32 s76, 13
	s_branch .LBB0_200
.Llast2_g2:
	s_setprio 0
	s_add_i32 s76, s76, 2
	s_add_u32 s56, s56, 0x100
	s_addc_u32 s57, s57, 0
	s_add_u32 s49, s49, 0x100
	s_addc_u32 s51, s51, 0
	s_cmp_gt_u32 s76, 13
	s_and_b64 vcc, exec, s[44:45]
	s_cbranch_vccz .LBB0_203
	s_barrier

; #define PG8_STAGE(bufoff, gbase, voff) do { _Pragma("unroll") for (int _i = 0; _i < 2; ++_i) \
;         __builtin_amdgcn_global_load_lds((const unsigned*)((const char*)(gbase) + (voff)[_i]), (PG8_LAS unsigned*)(lds + (bufoff) + ldsw + _i * 8192), 16, 0, 0); } while (0)
; #define PG8_LDA(dst, b, h) do { _Pragma("unroll") for (int m = 0; m < 4; ++m) _Pragma("unroll") for (int k = 0; k < 2; ++k) dst[m][k] = *(const PG8_LAS bf16x8*)(lds + PG8_SA(b, h) + aoff + m * 2048 + k * 1024); } while (0)
; #define PG8_LDB(dst, b, h) do { _Pragma("unroll") for (int n = 0; n < 2; ++n) _Pragma("unroll") for (int k = 0; k < 2; ++k) dst[n][k] = *(const PG8_LAS bf16x8*)(lds + PG8_SB(b, h) + boff + n * 2048 + k * 1024); } while (0)
; #define PG8_MMA(ai, bj, At, Bt) do { __builtin_amdgcn_s_setprio(1); _Pragma("unroll") for (int m = 0; m < 4; ++m) _Pragma("unroll") for (int n = 0; n < 2; ++n) _Pragma("unroll") for (int k = 0; k < 2; ++k) \
;         acc[ai][bj][m][n] = __builtin_amdgcn_mfma_f32_16x16x32_bf16(Bt[n][k], At[m][k], acc[ai][bj][m][n], 0, 0, 0); __builtin_amdgcn_s_setprio(0); } while (0)
; #define PG8_WAIT_V(n) asm volatile("s_waitcnt vmcnt(" #n ")" ::: "memory")
; #define PG8_WAIT_L(n) asm volatile("s_waitcnt lgkmcnt(" #n ")" ::: "memory")
; #define PG8_BAR __builtin_amdgcn_s_barrier()
; #define PG8_SCHED __builtin_amdgcn_sched_barrier(0)
; template <class Epi, class Sched, bool ALIGN_EPI = false, bool SP2 = false>
; __device__ __forceinline__ void gemm_phase(PG8_LAS unsigned char* lds, const Gemm g, const Sched& S, const Epi& E) {
;     ...
;             const bool last = (t == nt - 2);
;             const char* a1 = cA + (size_t)(t + 1) * kstep;
;             const char* a2 = last ? nA : cA + (size_t)(t + 2) * kstep; const char* b2 = last ? nB : cB + (size_t)(t + 2) * kstep;
;             const char* a3 = a2 + kstep; const char* b3 = b2 + kstep;
;             if (last && has_next) S.a_ready(nxt);
;             if constexpr (SP2) {
;             PG8_LDB(B0, 0, 0); PG8_LDB(B1, 0, 1); PG8_SCHED; PG8_LDA(At, 0, 0); PG8_STAGE(PG8_SA(1, 1), a1 + hstep, voffA);
;             PG8_WAIT_V(8); PG8_WAIT_L(0); PG8_BAR; PG8_MMA(0, 0, At, B0); PG8_MMA(0, 1, At, B1); PG8_BAR; PG8_SCHED;
;             PG8_LDA(At, 0, 1); PG8_STAGE(PG8_SB(0, 0), b2, voffB); PG8_STAGE(PG8_SB(0, 1), b2 + hstep, voffB); PG8_STAGE(PG8_SA(0, 0), a2, voffA);
.LBB0_488:
	s_add_u32 s10, s34, 0xfffc0080
	s_addc_u32 s11, s35, -1
	s_add_i32 s77, 0, 0x10000
	s_cmp_eq_u32 s76, 4
	s_cselect_b64 vcc, -1, 0
	s_cselect_b32 s53, s45, s11
	s_cselect_b32 s52, s44, s10
	s_cselect_b32 s51, s49, s75
	s_cselect_b32 s50, s48, s19
	s_add_i32 s78, 0, 0x14000
	v_add_u32_e32 v140, s77, v246
	v_add_u32_e32 v156, s77, v246
	v_add_u32_e32 v156, 0x1000, v156
	ds_read_b128 v[128:131], v140
	ds_read_b128 v[132:135], v140 offset:1024
	ds_read_b128 v[136:139], v140 offset:2048
	ds_read_b128 v[140:143], v140 offset:3072
	ds_read_b128 v[144:147], v156
	ds_read_b128 v[148:151], v156 offset:1024
	ds_read_b128 v[152:155], v156 offset:2048
	ds_read_b128 v[156:159], v156 offset:3072
	v_lshl_add_u64 v[208:209], s[34:35], 0, v[204:205]
	s_add_i32 m0, s55, 0xc000
	ds_read_b128 v[160:163], v249
	ds_read_b128 v[164:167], v249 offset:1024
	ds_read_b128 v[168:171], v249 offset:2048
	ds_read_b128 v[172:175], v249 offset:3072
	ds_read_b128 v[176:179], v249 offset:4096
	ds_read_b128 v[180:183], v249 offset:5120
	ds_read_b128 v[184:187], v249 offset:6144
	ds_read_b128 v[188:191], v249 offset:7168
	global_load_lds_dwordx4 v[208:209], off
	v_lshl_add_u64 v[208:209], s[34:35], 0, v[206:207]
	s_add_i32 m0, s55, 0xe000
	s_nop 0
	global_load_lds_dwordx4 v[208:209], off
	s_waitcnt vmcnt(8)
	s_waitcnt lgkmcnt(0)
	s_setprio 1
	s_barrier
	v_mfma_f32_16x16x32_bf16 v[124:127], v[128:131], v[160:163], v[124:127]
	v_mfma_f32_16x16x32_bf16 v[120:123], v[136:139], v[160:163], v[120:123]
	v_mfma_f32_16x16x32_bf16 v[116:119], v[128:131], v[168:171], v[116:119]
	v_mfma_f32_16x16x32_bf16 v[112:115], v[136:139], v[168:171], v[112:115]
	v_mfma_f32_16x16x32_bf16 v[108:111], v[128:131], v[176:179], v[108:111]
	v_mfma_f32_16x16x32_bf16 v[104:107], v[136:139], v[176:179], v[104:107]
	v_mfma_f32_16x16x32_bf16 v[100:103], v[128:131], v[184:187], v[100:103]
	v_mfma_f32_16x16x32_bf16 v[96:99], v[136:139], v[184:187], v[96:99]
	v_mfma_f32_16x16x32_bf16 v[124:127], v[132:135], v[164:167], v[124:127]
	v_mfma_f32_16x16x32_bf16 v[120:123], v[140:143], v[164:167], v[120:123]
	v_mfma_f32_16x16x32_bf16 v[116:119], v[132:135], v[172:175], v[116:119]
	v_mfma_f32_16x16x32_bf16 v[112:115], v[140:143], v[172:175], v[112:115]
	v_mfma_f32_16x16x32_bf16 v[108:111], v[132:135], v[180:183], v[108:111]
	v_mfma_f32_16x16x32_bf16 v[104:107], v[140:143], v[180:183], v[104:107]
	v_mfma_f32_16x16x32_bf16 v[100:103], v[132:135], v[188:191], v[100:103]
	v_mfma_f32_16x16x32_bf16 v[96:99], v[140:143], v[188:191], v[96:99]
	s_setprio 0
	s_setprio 1
	v_mfma_f32_16x16x32_bf16 v[92:95], v[144:147], v[160:163], v[92:95]
	v_mfma_f32_16x16x32_bf16 v[88:91], v[152:155], v[160:163], v[88:91]
	v_mfma_f32_16x16x32_bf16 v[84:87], v[144:147], v[168:171], v[84:87]
	v_mfma_f32_16x16x32_bf16 v[80:83], v[152:155], v[168:171], v[80:83]
	v_mfma_f32_16x16x32_bf16 v[76:79], v[144:147], v[176:179], v[76:79]
	v_mfma_f32_16x16x32_bf16 v[72:75], v[152:155], v[176:179], v[72:75]
	v_mfma_f32_16x16x32_bf16 v[68:71], v[144:147], v[184:187], v[68:71]
	v_mfma_f32_16x16x32_bf16 v[64:67], v[152:155], v[184:187], v[64:67]
	v_mfma_f32_16x16x32_bf16 v[92:95], v[148:151], v[164:167], v[92:95]
	v_mfma_f32_16x16x32_bf16 v[88:91], v[156:159], v[164:167], v[88:91]
	v_mfma_f32_16x16x32_bf16 v[84:87], v[148:151], v[172:175], v[84:87]
	v_mfma_f32_16x16x32_bf16 v[80:83], v[156:159], v[172:175], v[80:83]
	v_mfma_f32_16x16x32_bf16 v[76:79], v[148:151], v[180:183], v[76:79]
	v_mfma_f32_16x16x32_bf16 v[72:75], v[156:159], v[180:183], v[72:75]
	v_mfma_f32_16x16x32_bf16 v[68:71], v[148:151], v[188:191], v[68:71]
	v_mfma_f32_16x16x32_bf16 v[64:67], v[156:159], v[188:191], v[64:67]
	s_barrier
	s_setprio 0
	s_add_i32 s10, s77, s14
	v_lshl_add_u64 v[208:209], s[50:51], 0, v[198:199]
	s_mov_b32 m0, s10
	ds_read_b128 v[160:163], v249 offset:16384
	ds_read_b128 v[164:167], v249 offset:17408
	ds_read_b128 v[168:171], v249 offset:18432
	ds_read_b128 v[172:175], v249 offset:19456
	ds_read_b128 v[176:179], v249 offset:20480
	ds_read_b128 v[180:183], v249 offset:21504
	ds_read_b128 v[184:187], v249 offset:22528
	ds_read_b128 v[188:191], v249 offset:23552
	global_load_lds_dwordx4 v[208:209], off
	s_add_i32 m0, s10, 0x2000
	s_add_u32 s10, s50, 0x40000
	v_lshl_add_u64 v[210:211], s[50:51], 0, v[194:195]
	s_addc_u32 s11, s51, 0
	s_add_i32 s77, s78, s14
	global_load_lds_dwordx4 v[210:211], off
	v_lshl_add_u64 v[212:213], s[10:11], 0, v[198:199]
	s_mov_b32 m0, s77
	v_lshl_add_u64 v[214:215], s[52:53], 0, v[196:197]
	global_load_lds_dwordx4 v[212:213], off
	v_lshl_add_u64 v[212:213], s[10:11], 0, v[194:195]
	s_add_i32 m0, s77, 0x2000
	s_nop 0
	global_load_lds_dwordx4 v[212:213], off
	v_lshl_add_u64 v[212:213], s[52:53], 0, v[200:201]
	s_mov_b32 m0, s55
	s_nop 0
	global_load_lds_dwordx4 v[212:213], off
	s_mov_b32 m0, s58
	s_nop 0
	global_load_lds_dwordx4 v[214:215], off
	s_waitcnt vmcnt(8)
	s_waitcnt lgkmcnt(0)
	s_setprio 1
	s_barrier
; #define PG8_STAGE(bufoff, gbase, voff) do { _Pragma("unroll") for (int _i = 0; _i < 2; ++_i) \
;         __builtin_amdgcn_global_load_lds((const unsigned*)((const char*)(gbase) + (voff)[_i]), (PG8_LAS unsigned*)(lds + (bufoff) + ldsw + _i * 8192), 16, 0, 0); } while (0)
; #define PG8_LDA(dst, b, h) do { _Pragma("unroll") for (int m = 0; m < 4; ++m) _Pragma("unroll") for (int k = 0; k < 2; ++k) dst[m][k] = *(const PG8_LAS bf16x8*)(lds + PG8_SA(b, h) + aoff + m * 2048 + k * 1024); } while (0)
; #define PG8_LDB(dst, b, h) do { _Pragma("unroll") for (int n = 0; n < 2; ++n) _Pragma("unroll") for (int k = 0; k < 2; ++k) dst[n][k] = *(const PG8_LAS bf16x8*)(lds + PG8_SB(b, h) + boff + n * 2048 + k * 1024); } while (0)
; #define PG8_MMA(ai, bj, At, Bt) do { __builtin_amdgcn_s_setprio(1); _Pragma("unroll") for (int m = 0; m < 4; ++m) _Pragma("unroll") for (int n = 0; n < 2; ++n) _Pragma("unroll") for (int k = 0; k < 2; ++k) \
;         acc[ai][bj][m][n] = __builtin_amdgcn_mfma_f32_16x16x32_bf16(Bt[n][k], At[m][k], acc[ai][bj][m][n], 0, 0, 0); __builtin_amdgcn_s_setprio(0); } while (0)
; #define PG8_WAIT_V(n) asm volatile("s_waitcnt vmcnt(" #n ")" ::: "memory")
; #define PG8_WAIT_L(n) asm volatile("s_waitcnt lgkmcnt(" #n ")" ::: "memory")
; #define PG8_BAR __builtin_amdgcn_s_barrier()
; #define PG8_SCHED __builtin_amdgcn_sched_barrier(0)
; template <class Epi, class Sched, bool ALIGN_EPI = false, bool SP2 = false>
; __device__ __forceinline__ void gemm_phase(PG8_LAS unsigned char* lds, const Gemm g, const Sched& S, const Epi& E) {
;     ...
;             PG8_WAIT_V(8); PG8_WAIT_L(0); PG8_BAR; PG8_MMA(1, 0, At, B0); PG8_MMA(1, 1, At, B1); PG8_BAR; PG8_SCHED;
;             PG8_LDB(B0, 1, 0); PG8_LDB(B1, 1, 1); PG8_SCHED; PG8_LDA(At, 1, 0); PG8_STAGE(PG8_SA(0, 1), a2 + hstep, voffA);
;             PG8_WAIT_V(8); PG8_WAIT_L(0); PG8_BAR; PG8_MMA(0, 0, At, B0); PG8_MMA(0, 1, At, B1); PG8_BAR; PG8_SCHED;
	v_mfma_f32_16x16x32_bf16 v[60:63], v[128:131], v[160:163], v[60:63]
	v_mfma_f32_16x16x32_bf16 v[56:59], v[136:139], v[160:163], v[56:59]
	v_mfma_f32_16x16x32_bf16 v[52:55], v[128:131], v[168:171], v[52:55]
	v_mfma_f32_16x16x32_bf16 v[48:51], v[136:139], v[168:171], v[48:51]
	v_mfma_f32_16x16x32_bf16 v[44:47], v[128:131], v[176:179], v[44:47]
	v_mfma_f32_16x16x32_bf16 v[40:43], v[136:139], v[176:179], v[40:43]
	v_mfma_f32_16x16x32_bf16 v[36:39], v[128:131], v[184:187], v[36:39]
	v_mfma_f32_16x16x32_bf16 v[32:35], v[136:139], v[184:187], v[32:35]
	v_mfma_f32_16x16x32_bf16 v[60:63], v[132:135], v[164:167], v[60:63]
	v_mfma_f32_16x16x32_bf16 v[56:59], v[140:143], v[164:167], v[56:59]
	v_mfma_f32_16x16x32_bf16 v[52:55], v[132:135], v[172:175], v[52:55]
	v_mfma_f32_16x16x32_bf16 v[48:51], v[140:143], v[172:175], v[48:51]
	v_mfma_f32_16x16x32_bf16 v[44:47], v[132:135], v[180:183], v[44:47]
	v_mfma_f32_16x16x32_bf16 v[40:43], v[140:143], v[180:183], v[40:43]
	v_mfma_f32_16x16x32_bf16 v[36:39], v[132:135], v[188:191], v[36:39]
	v_mfma_f32_16x16x32_bf16 v[32:35], v[140:143], v[188:191], v[32:35]
	s_setprio 0
	s_setprio 1
	v_mfma_f32_16x16x32_bf16 v[28:31], v[144:147], v[160:163], v[28:31]
	v_mfma_f32_16x16x32_bf16 v[24:27], v[152:155], v[160:163], v[24:27]
	v_mfma_f32_16x16x32_bf16 v[20:23], v[144:147], v[168:171], v[20:23]
	v_mfma_f32_16x16x32_bf16 v[16:19], v[152:155], v[168:171], v[16:19]
	v_mfma_f32_16x16x32_bf16 v[12:15], v[144:147], v[176:179], v[12:15]
	v_mfma_f32_16x16x32_bf16 v[8:11], v[152:155], v[176:179], v[8:11]
	v_mfma_f32_16x16x32_bf16 v[4:7], v[144:147], v[184:187], v[4:7]
	v_mfma_f32_16x16x32_bf16 v[0:3], v[152:155], v[184:187], v[0:3]
	v_mfma_f32_16x16x32_bf16 v[28:31], v[148:151], v[164:167], v[28:31]
	v_mfma_f32_16x16x32_bf16 v[24:27], v[156:159], v[164:167], v[24:27]
	v_mfma_f32_16x16x32_bf16 v[20:23], v[148:151], v[172:175], v[20:23]
	v_mfma_f32_16x16x32_bf16 v[16:19], v[156:159], v[172:175], v[16:19]
	v_mfma_f32_16x16x32_bf16 v[12:15], v[148:151], v[180:183], v[12:15]
	v_mfma_f32_16x16x32_bf16 v[8:11], v[156:159], v[180:183], v[8:11]
	v_mfma_f32_16x16x32_bf16 v[4:7], v[148:151], v[188:191], v[4:7]
	v_mfma_f32_16x16x32_bf16 v[0:3], v[156:159], v[188:191], v[0:3]
	s_barrier
	s_setprio 0
	s_add_i32 s77, 0, 0x18000
	s_add_i32 s78, 0, 0x1c000
	v_add_u32_e32 v140, s77, v246
	v_add_u32_e32 v156, s77, v246
	v_add_u32_e32 v156, 0x1000, v156
	ds_read_b128 v[128:131], v140
	ds_read_b128 v[132:135], v140 offset:1024
	ds_read_b128 v[136:139], v140 offset:2048
	ds_read_b128 v[140:143], v140 offset:3072
	ds_read_b128 v[144:147], v156
	ds_read_b128 v[148:151], v156 offset:1024
	ds_read_b128 v[152:155], v156 offset:2048
	ds_read_b128 v[156:159], v156 offset:3072
	s_add_u32 s10, s52, 0x40000
	s_addc_u32 s11, s53, 0
	s_mov_b32 m0, s59
	v_lshl_add_u64 v[216:217], s[10:11], 0, v[200:201]
	ds_read_b128 v[160:163], v249 offset:32768
	ds_read_b128 v[164:167], v249 offset:33792
	ds_read_b128 v[168:171], v249 offset:34816
	ds_read_b128 v[172:175], v249 offset:35840
	ds_read_b128 v[176:179], v249 offset:36864
	ds_read_b128 v[180:183], v249 offset:37888
	ds_read_b128 v[184:187], v249 offset:38912
	ds_read_b128 v[188:191], v249 offset:39936
	global_load_lds_dwordx4 v[216:217], off
	v_lshl_add_u64 v[216:217], s[10:11], 0, v[196:197]
	s_mov_b32 m0, s60
	s_nop 0
	global_load_lds_dwordx4 v[216:217], off
	s_waitcnt vmcnt(8)
	s_waitcnt lgkmcnt(0)
	s_setprio 1
	s_barrier
	v_mfma_f32_16x16x32_bf16 v[124:127], v[128:131], v[160:163], v[124:127]
	v_mfma_f32_16x16x32_bf16 v[120:123], v[136:139], v[160:163], v[120:123]
	v_mfma_f32_16x16x32_bf16 v[116:119], v[128:131], v[168:171], v[116:119]
	v_mfma_f32_16x16x32_bf16 v[112:115], v[136:139], v[168:171], v[112:115]
	v_mfma_f32_16x16x32_bf16 v[108:111], v[128:131], v[176:179], v[108:111]
	v_mfma_f32_16x16x32_bf16 v[104:107], v[136:139], v[176:179], v[104:107]
	v_mfma_f32_16x16x32_bf16 v[100:103], v[128:131], v[184:187], v[100:103]
	v_mfma_f32_16x16x32_bf16 v[96:99], v[136:139], v[184:187], v[96:99]
	v_mfma_f32_16x16x32_bf16 v[124:127], v[132:135], v[164:167], v[124:127]
	v_mfma_f32_16x16x32_bf16 v[120:123], v[140:143], v[164:167], v[120:123]
	v_mfma_f32_16x16x32_bf16 v[116:119], v[132:135], v[172:175], v[116:119]
	v_mfma_f32_16x16x32_bf16 v[112:115], v[140:143], v[172:175], v[112:115]
	v_mfma_f32_16x16x32_bf16 v[108:111], v[132:135], v[180:183], v[108:111]
	v_mfma_f32_16x16x32_bf16 v[104:107], v[140:143], v[180:183], v[104:107]
	v_mfma_f32_16x16x32_bf16 v[100:103], v[132:135], v[188:191], v[100:103]
	v_mfma_f32_16x16x32_bf16 v[96:99], v[140:143], v[188:191], v[96:99]
	s_setprio 0
	s_setprio 1
	v_mfma_f32_16x16x32_bf16 v[92:95], v[144:147], v[160:163], v[92:95]
	v_mfma_f32_16x16x32_bf16 v[88:91], v[152:155], v[160:163], v[88:91]
	v_mfma_f32_16x16x32_bf16 v[84:87], v[144:147], v[168:171], v[84:87]
	v_mfma_f32_16x16x32_bf16 v[80:83], v[152:155], v[168:171], v[80:83]
	v_mfma_f32_16x16x32_bf16 v[76:79], v[144:147], v[176:179], v[76:79]
	v_mfma_f32_16x16x32_bf16 v[72:75], v[152:155], v[176:179], v[72:75]
	v_mfma_f32_16x16x32_bf16 v[68:71], v[144:147], v[184:187], v[68:71]
	v_mfma_f32_16x16x32_bf16 v[64:67], v[152:155], v[184:187], v[64:67]
	v_mfma_f32_16x16x32_bf16 v[92:95], v[148:151], v[164:167], v[92:95]
	v_mfma_f32_16x16x32_bf16 v[88:91], v[156:159], v[164:167], v[88:91]
	v_mfma_f32_16x16x32_bf16 v[84:87], v[148:151], v[172:175], v[84:87]
	v_mfma_f32_16x16x32_bf16 v[80:83], v[156:159], v[172:175], v[80:83]
	v_mfma_f32_16x16x32_bf16 v[76:79], v[148:151], v[180:183], v[76:79]
	v_mfma_f32_16x16x32_bf16 v[72:75], v[156:159], v[180:183], v[72:75]
	v_mfma_f32_16x16x32_bf16 v[68:71], v[148:151], v[188:191], v[68:71]
	v_mfma_f32_16x16x32_bf16 v[64:67], v[156:159], v[188:191], v[64:67]
	s_barrier
; #define PG8_STAGE(bufoff, gbase, voff) do { _Pragma("unroll") for (int _i = 0; _i < 2; ++_i) \
;         __builtin_amdgcn_global_load_lds((const unsigned*)((const char*)(gbase) + (voff)[_i]), (PG8_LAS unsigned*)(lds + (bufoff) + ldsw + _i * 8192), 16, 0, 0); } while (0)
; #define PG8_LDA(dst, b, h) do { _Pragma("unroll") for (int m = 0; m < 4; ++m) _Pragma("unroll") for (int k = 0; k < 2; ++k) dst[m][k] = *(const PG8_LAS bf16x8*)(lds + PG8_SA(b, h) + aoff + m * 2048 + k * 1024); } while (0)
; #define PG8_MMA(ai, bj, At, Bt) do { __builtin_amdgcn_s_setprio(1); _Pragma("unroll") for (int m = 0; m < 4; ++m) _Pragma("unroll") for (int n = 0; n < 2; ++n) _Pragma("unroll") for (int k = 0; k < 2; ++k) \
;         acc[ai][bj][m][n] = __builtin_amdgcn_mfma_f32_16x16x32_bf16(Bt[n][k], At[m][k], acc[ai][bj][m][n], 0, 0, 0); __builtin_amdgcn_s_setprio(0); } while (0)
; #define PG8_WAIT_V(n) asm volatile("s_waitcnt vmcnt(" #n ")" ::: "memory")
; #define PG8_WAIT_L(n) asm volatile("s_waitcnt lgkmcnt(" #n ")" ::: "memory")
; #define PG8_BAR __builtin_amdgcn_s_barrier()
; #define PG8_SCHED __builtin_amdgcn_sched_barrier(0)
; template <class Epi, class Sched, bool ALIGN_EPI = false, bool SP2 = false>
; __device__ __forceinline__ void gemm_phase(PG8_LAS unsigned char* lds, const Gemm g, const Sched& S, const Epi& E) {
;     ...
;             PG8_LDA(At, 1, 1); PG8_STAGE(PG8_SB(1, 0), b3, voffB); PG8_STAGE(PG8_SB(1, 1), b3 + hstep, voffB); PG8_STAGE(PG8_SA(1, 0), a3, voffA);
;             PG8_WAIT_V(8); PG8_WAIT_L(0); PG8_BAR; PG8_MMA(1, 0, At, B0); PG8_MMA(1, 1, At, B1); PG8_BAR; PG8_SCHED;
;     ...
;         if constexpr (ALIGN_EPI) { if (wr == 0) PG8_BAR; }
	s_setprio 0
	s_add_i32 s10, s77, s14
	v_lshl_add_u64 v[208:209], v[208:209], 0, s[36:37]
	s_mov_b32 m0, s10
	ds_read_b128 v[160:163], v249 offset:49152
	ds_read_b128 v[164:167], v249 offset:50176
	ds_read_b128 v[168:171], v249 offset:51200
	ds_read_b128 v[172:175], v249 offset:52224
	ds_read_b128 v[176:179], v249 offset:53248
	ds_read_b128 v[180:183], v249 offset:54272
	ds_read_b128 v[184:187], v249 offset:55296
	ds_read_b128 v[188:191], v249 offset:56320
	global_load_lds_dwordx4 v[208:209], off
	s_add_i32 m0, s10, 0x2000
	s_add_u32 s10, s50, 0x40080
	v_lshl_add_u64 v[208:209], v[210:211], 0, s[36:37]
	s_addc_u32 s11, s51, 0
	s_add_i32 s50, s78, s14
	global_load_lds_dwordx4 v[208:209], off
	v_lshl_add_u64 v[208:209], s[10:11], 0, v[198:199]
	s_mov_b32 m0, s50
	s_nop 0
	global_load_lds_dwordx4 v[208:209], off
	v_lshl_add_u64 v[208:209], s[10:11], 0, v[194:195]
	s_add_i32 m0, s50, 0x2000
	s_nop 0
	global_load_lds_dwordx4 v[208:209], off
	v_lshl_add_u64 v[208:209], v[212:213], 0, s[36:37]
	s_mov_b32 m0, s65
	s_nop 0
	global_load_lds_dwordx4 v[208:209], off
	v_lshl_add_u64 v[208:209], v[214:215], 0, s[36:37]
	s_mov_b32 m0, s66
	s_nop 0
	global_load_lds_dwordx4 v[208:209], off
	s_waitcnt vmcnt(8)
	s_waitcnt lgkmcnt(0)
	s_setprio 1
	s_barrier
	v_mfma_f32_16x16x32_bf16 v[60:63], v[128:131], v[160:163], v[60:63]
	v_mfma_f32_16x16x32_bf16 v[56:59], v[136:139], v[160:163], v[56:59]
	v_mfma_f32_16x16x32_bf16 v[52:55], v[128:131], v[168:171], v[52:55]
	v_mfma_f32_16x16x32_bf16 v[48:51], v[136:139], v[168:171], v[48:51]
	v_mfma_f32_16x16x32_bf16 v[44:47], v[128:131], v[176:179], v[44:47]
	v_mfma_f32_16x16x32_bf16 v[40:43], v[136:139], v[176:179], v[40:43]
	v_mfma_f32_16x16x32_bf16 v[36:39], v[128:131], v[184:187], v[36:39]
	v_mfma_f32_16x16x32_bf16 v[32:35], v[136:139], v[184:187], v[32:35]
	v_mfma_f32_16x16x32_bf16 v[60:63], v[132:135], v[164:167], v[60:63]
	v_mfma_f32_16x16x32_bf16 v[56:59], v[140:143], v[164:167], v[56:59]
	v_mfma_f32_16x16x32_bf16 v[52:55], v[132:135], v[172:175], v[52:55]
	v_mfma_f32_16x16x32_bf16 v[48:51], v[140:143], v[172:175], v[48:51]
	v_mfma_f32_16x16x32_bf16 v[44:47], v[132:135], v[180:183], v[44:47]
	v_mfma_f32_16x16x32_bf16 v[40:43], v[140:143], v[180:183], v[40:43]
	v_mfma_f32_16x16x32_bf16 v[36:39], v[132:135], v[188:191], v[36:39]
	v_mfma_f32_16x16x32_bf16 v[32:35], v[140:143], v[188:191], v[32:35]
	s_setprio 0
	s_setprio 1
	v_mfma_f32_16x16x32_bf16 v[28:31], v[144:147], v[160:163], v[28:31]
	v_mfma_f32_16x16x32_bf16 v[24:27], v[152:155], v[160:163], v[24:27]
	v_mfma_f32_16x16x32_bf16 v[20:23], v[144:147], v[168:171], v[20:23]
	v_mfma_f32_16x16x32_bf16 v[16:19], v[152:155], v[168:171], v[16:19]
	v_mfma_f32_16x16x32_bf16 v[12:15], v[144:147], v[176:179], v[12:15]
	v_mfma_f32_16x16x32_bf16 v[8:11], v[152:155], v[176:179], v[8:11]
	v_mfma_f32_16x16x32_bf16 v[4:7], v[144:147], v[184:187], v[4:7]
	v_mfma_f32_16x16x32_bf16 v[0:3], v[152:155], v[184:187], v[0:3]
	v_mfma_f32_16x16x32_bf16 v[28:31], v[148:151], v[164:167], v[28:31]
	v_mfma_f32_16x16x32_bf16 v[24:27], v[156:159], v[164:167], v[24:27]
	v_mfma_f32_16x16x32_bf16 v[20:23], v[148:151], v[172:175], v[20:23]
	v_mfma_f32_16x16x32_bf16 v[16:19], v[156:159], v[172:175], v[16:19]
	v_mfma_f32_16x16x32_bf16 v[12:15], v[148:151], v[180:183], v[12:15]
	v_mfma_f32_16x16x32_bf16 v[8:11], v[156:159], v[180:183], v[8:11]
	v_mfma_f32_16x16x32_bf16 v[4:7], v[148:151], v[188:191], v[4:7]
	v_mfma_f32_16x16x32_bf16 v[0:3], v[156:159], v[188:191], v[0:3]
	s_cbranch_vccnz .Llast2_g3
	s_barrier
	s_setprio 0
	s_add_i32 s76, s76, 2
	s_add_u32 s34, s34, 0x100
	s_addc_u32 s35, s35, 0
	s_add_u32 s19, s19, 0x100
	s_addc_u32 s75, s75, 0
	s_cmp_gt_u32 s76, 5
	s_branch .LBB0_488
.Llast2_g3:
	s_setprio 0
	s_add_i32 s76, s76, 2
	s_add_u32 s34, s34, 0x100
	s_addc_u32 s35, s35, 0
	s_add_u32 s19, s19, 0x100
	s_addc_u32 s75, s75, 0
	s_cmp_gt_u32 s76, 5
	s_and_b64 vcc, exec, s[24:25]
	s_cbranch_vccz .LBB0_491
	s_barrier

; #define PG8_STAGE(bufoff, gbase, voff) do { _Pragma("unroll") for (int _i = 0; _i < 2; ++_i) \
;         __builtin_amdgcn_global_load_lds((const unsigned*)((const char*)(gbase) + (voff)[_i]), (PG8_LAS unsigned*)(lds + (bufoff) + ldsw + _i * 8192), 16, 0, 0); } while (0)
; #define PG8_LDA(dst, b, h) do { _Pragma("unroll") for (int m = 0; m < 4; ++m) _Pragma("unroll") for (int k = 0; k < 2; ++k) dst[m][k] = *(const PG8_LAS bf16x8*)(lds + PG8_SA(b, h) + aoff + m * 2048 + k * 1024); } while (0)
; #define PG8_LDB(dst, b, h) do { _Pragma("unroll") for (int n = 0; n < 2; ++n) _Pragma("unroll") for (int k = 0; k < 2; ++k) dst[n][k] = *(const PG8_LAS bf16x8*)(lds + PG8_SB(b, h) + boff + n * 2048 + k * 1024); } while (0)
; #define PG8_MMA(ai, bj, At, Bt) do { __builtin_amdgcn_s_setprio(1); _Pragma("unroll") for (int m = 0; m < 4; ++m) _Pragma("unroll") for (int n = 0; n < 2; ++n) _Pragma("unroll") for (int k = 0; k < 2; ++k) \
;         acc[ai][bj][m][n] = __builtin_amdgcn_mfma_f32_16x16x32_bf16(Bt[n][k], At[m][k], acc[ai][bj][m][n], 0, 0, 0); __builtin_amdgcn_s_setprio(0); } while (0)
; #define PG8_WAIT_V(n) asm volatile("s_waitcnt vmcnt(" #n ")" ::: "memory")
; #define PG8_WAIT_L(n) asm volatile("s_waitcnt lgkmcnt(" #n ")" ::: "memory")
; #define PG8_BAR __builtin_amdgcn_s_barrier()
; #define PG8_SCHED __builtin_amdgcn_sched_barrier(0)
; template <class Epi, class Sched, bool ALIGN_EPI = false, bool SP2 = false>
; __device__ __forceinline__ void gemm_phase(PG8_LAS unsigned char* lds, const Gemm g, const Sched& S, const Epi& E) {
;     ...
;             const bool last = (t == nt - 2);
;             const char* a1 = cA + (size_t)(t + 1) * kstep;
;             const char* a2 = last ? nA : cA + (size_t)(t + 2) * kstep; const char* b2 = last ? nB : cB + (size_t)(t + 2) * kstep;
;             const char* a3 = a2 + kstep; const char* b3 = b2 + kstep;
;             if (last && has_next) S.a_ready(nxt);
;             if constexpr (SP2) {
;             PG8_LDB(B0, 0, 0); PG8_LDB(B1, 0, 1); PG8_SCHED; PG8_LDA(At, 0, 0); PG8_STAGE(PG8_SA(1, 1), a1 + hstep, voffA);
;             PG8_WAIT_V(8); PG8_WAIT_L(0); PG8_BAR; PG8_MMA(0, 0, At, B0); PG8_MMA(0, 1, At, B1); PG8_BAR; PG8_SCHED;
;             PG8_LDA(At, 0, 1); PG8_STAGE(PG8_SB(0, 0), b2, voffB); PG8_STAGE(PG8_SB(0, 1), b2 + hstep, voffB); PG8_STAGE(PG8_SA(0, 0), a2, voffA);
.LBB0_577:
	s_add_u32 s10, s44, 0xfffc0080
	s_addc_u32 s11, s45, -1
	s_add_i32 s64, 0, 0x10000
	s_cmp_eq_u32 s63, 12
	s_cselect_b64 vcc, -1, 0
	s_cselect_b32 s49, s29, s11
	s_cselect_b32 s48, s43, s10
	v_add_u32_e32 v146, s64, v149
	s_cselect_b32 s47, s27, s62
	s_cselect_b32 s46, s60, s61
	s_add_i32 s65, 0, 0x14000
	ds_read_b128 v[128:131], v146
	ds_read_b128 v[154:157], v146 offset:1024
	ds_read_b128 v[158:161], v146 offset:2048
	ds_read_b128 v[162:165], v146 offset:3072
	v_add_u32_e32 v146, s65, v149
	ds_read_b128 v[166:169], v146
	ds_read_b128 v[170:173], v146 offset:1024
	ds_read_b128 v[174:177], v146 offset:2048
	ds_read_b128 v[178:181], v146 offset:3072
	v_lshl_add_u64 v[190:191], s[44:45], 0, v[142:143]
	s_add_i32 m0, s51, 0xc000
	ds_read_b128 v[182:185], v153
	ds_read_b128 v[186:189], v153 offset:1024
	ds_read_b128 v[194:197], v153 offset:2048
	ds_read_b128 v[198:201], v153 offset:3072
	ds_read_b128 v[202:205], v153 offset:4096
	ds_read_b128 v[206:209], v153 offset:5120
	ds_read_b128 v[210:213], v153 offset:6144
	ds_read_b128 v[214:217], v153 offset:7168
	global_load_lds_dwordx4 v[190:191], off
	v_lshl_add_u64 v[190:191], s[44:45], 0, v[144:145]
	s_add_i32 m0, s51, 0xe000
	s_nop 0
	global_load_lds_dwordx4 v[190:191], off
	s_waitcnt vmcnt(8)
	s_waitcnt lgkmcnt(0)
	s_setprio 1
	s_barrier
	v_mfma_f32_16x16x32_bf16 v[124:127], v[128:131], v[182:185], v[124:127]
	v_mfma_f32_16x16x32_bf16 v[116:119], v[158:161], v[182:185], v[116:119]
	v_mfma_f32_16x16x32_bf16 v[108:111], v[128:131], v[194:197], v[108:111]
	v_mfma_f32_16x16x32_bf16 v[100:103], v[158:161], v[194:197], v[100:103]
	v_mfma_f32_16x16x32_bf16 v[92:95], v[128:131], v[202:205], v[92:95]
	v_mfma_f32_16x16x32_bf16 v[84:87], v[158:161], v[202:205], v[84:87]
	v_mfma_f32_16x16x32_bf16 v[76:79], v[128:131], v[210:213], v[76:79]
	v_mfma_f32_16x16x32_bf16 v[68:71], v[158:161], v[210:213], v[68:71]
	v_mfma_f32_16x16x32_bf16 v[124:127], v[154:157], v[186:189], v[124:127]
	v_mfma_f32_16x16x32_bf16 v[116:119], v[162:165], v[186:189], v[116:119]
	v_mfma_f32_16x16x32_bf16 v[108:111], v[154:157], v[198:201], v[108:111]
	v_mfma_f32_16x16x32_bf16 v[100:103], v[162:165], v[198:201], v[100:103]
	v_mfma_f32_16x16x32_bf16 v[92:95], v[154:157], v[206:209], v[92:95]
	v_mfma_f32_16x16x32_bf16 v[84:87], v[162:165], v[206:209], v[84:87]
	v_mfma_f32_16x16x32_bf16 v[76:79], v[154:157], v[214:217], v[76:79]
	v_mfma_f32_16x16x32_bf16 v[68:71], v[162:165], v[214:217], v[68:71]
	s_setprio 0
	s_setprio 1
	v_mfma_f32_16x16x32_bf16 v[120:123], v[166:169], v[182:185], v[120:123]
	v_mfma_f32_16x16x32_bf16 v[112:115], v[174:177], v[182:185], v[112:115]
	v_mfma_f32_16x16x32_bf16 v[104:107], v[166:169], v[194:197], v[104:107]
	v_mfma_f32_16x16x32_bf16 v[96:99], v[174:177], v[194:197], v[96:99]
	v_mfma_f32_16x16x32_bf16 v[88:91], v[166:169], v[202:205], v[88:91]
	v_mfma_f32_16x16x32_bf16 v[80:83], v[174:177], v[202:205], v[80:83]
	v_mfma_f32_16x16x32_bf16 v[72:75], v[166:169], v[210:213], v[72:75]
	v_mfma_f32_16x16x32_bf16 v[64:67], v[174:177], v[210:213], v[64:67]
	v_mfma_f32_16x16x32_bf16 v[120:123], v[170:173], v[186:189], v[120:123]
	v_mfma_f32_16x16x32_bf16 v[112:115], v[178:181], v[186:189], v[112:115]
	v_mfma_f32_16x16x32_bf16 v[104:107], v[170:173], v[198:201], v[104:107]
	v_mfma_f32_16x16x32_bf16 v[96:99], v[178:181], v[198:201], v[96:99]
	v_mfma_f32_16x16x32_bf16 v[88:91], v[170:173], v[206:209], v[88:91]
	v_mfma_f32_16x16x32_bf16 v[80:83], v[178:181], v[206:209], v[80:83]
	v_mfma_f32_16x16x32_bf16 v[72:75], v[170:173], v[214:217], v[72:75]
	v_mfma_f32_16x16x32_bf16 v[64:67], v[178:181], v[214:217], v[64:67]
	s_barrier
	s_setprio 0
	s_add_i32 s10, s64, s19
	v_lshl_add_u64 v[190:191], s[46:47], 0, v[136:137]
	s_mov_b32 m0, s10
	ds_read_b128 v[182:185], v153 offset:16384
	ds_read_b128 v[186:189], v153 offset:17408
	ds_read_b128 v[194:197], v153 offset:18432
	ds_read_b128 v[198:201], v153 offset:19456
	ds_read_b128 v[202:205], v153 offset:20480
	ds_read_b128 v[206:209], v153 offset:21504
	ds_read_b128 v[210:213], v153 offset:22528
	ds_read_b128 v[214:217], v153 offset:23552
	global_load_lds_dwordx4 v[190:191], off
	s_add_i32 m0, s10, 0x2000
	s_add_u32 s10, s46, 0x40000
	v_lshl_add_u64 v[218:219], s[46:47], 0, v[132:133]
	s_addc_u32 s11, s47, 0
	s_add_i32 s64, s65, s19
	global_load_lds_dwordx4 v[218:219], off
	v_lshl_add_u64 v[220:221], s[10:11], 0, v[136:137]
	s_mov_b32 m0, s64
	v_lshl_add_u64 v[222:223], s[48:49], 0, v[134:135]
	global_load_lds_dwordx4 v[220:221], off
	v_lshl_add_u64 v[220:221], s[10:11], 0, v[132:133]
	s_add_i32 m0, s64, 0x2000
	s_nop 0
	global_load_lds_dwordx4 v[220:221], off
	v_lshl_add_u64 v[220:221], s[48:49], 0, v[138:139]
	s_mov_b32 m0, s51
	s_nop 0
	global_load_lds_dwordx4 v[220:221], off
	s_mov_b32 m0, s52
	s_nop 0
	global_load_lds_dwordx4 v[222:223], off
	s_waitcnt vmcnt(8)
	s_waitcnt lgkmcnt(0)
	s_setprio 1
	s_barrier
; #define PG8_STAGE(bufoff, gbase, voff) do { _Pragma("unroll") for (int _i = 0; _i < 2; ++_i) \
;         __builtin_amdgcn_global_load_lds((const unsigned*)((const char*)(gbase) + (voff)[_i]), (PG8_LAS unsigned*)(lds + (bufoff) + ldsw + _i * 8192), 16, 0, 0); } while (0)
; #define PG8_LDA(dst, b, h) do { _Pragma("unroll") for (int m = 0; m < 4; ++m) _Pragma("unroll") for (int k = 0; k < 2; ++k) dst[m][k] = *(const PG8_LAS bf16x8*)(lds + PG8_SA(b, h) + aoff + m * 2048 + k * 1024); } while (0)
; #define PG8_LDB(dst, b, h) do { _Pragma("unroll") for (int n = 0; n < 2; ++n) _Pragma("unroll") for (int k = 0; k < 2; ++k) dst[n][k] = *(const PG8_LAS bf16x8*)(lds + PG8_SB(b, h) + boff + n * 2048 + k * 1024); } while (0)
; #define PG8_MMA(ai, bj, At, Bt) do { __builtin_amdgcn_s_setprio(1); _Pragma("unroll") for (int m = 0; m < 4; ++m) _Pragma("unroll") for (int n = 0; n < 2; ++n) _Pragma("unroll") for (int k = 0; k < 2; ++k) \
;         acc[ai][bj][m][n] = __builtin_amdgcn_mfma_f32_16x16x32_bf16(Bt[n][k], At[m][k], acc[ai][bj][m][n], 0, 0, 0); __builtin_amdgcn_s_setprio(0); } while (0)
; #define PG8_WAIT_V(n) asm volatile("s_waitcnt vmcnt(" #n ")" ::: "memory")
; #define PG8_WAIT_L(n) asm volatile("s_waitcnt lgkmcnt(" #n ")" ::: "memory")
; #define PG8_BAR __builtin_amdgcn_s_barrier()
; #define PG8_SCHED __builtin_amdgcn_sched_barrier(0)
; template <class Epi, class Sched, bool ALIGN_EPI = false, bool SP2 = false>
; __device__ __forceinline__ void gemm_phase(PG8_LAS unsigned char* lds, const Gemm g, const Sched& S, const Epi& E) {
;     ...
;             PG8_WAIT_V(8); PG8_WAIT_L(0); PG8_BAR; PG8_MMA(1, 0, At, B0); PG8_MMA(1, 1, At, B1); PG8_BAR; PG8_SCHED;
;             PG8_LDB(B0, 1, 0); PG8_LDB(B1, 1, 1); PG8_SCHED; PG8_LDA(At, 1, 0); PG8_STAGE(PG8_SA(0, 1), a2 + hstep, voffA);
;             PG8_WAIT_V(8); PG8_WAIT_L(0); PG8_BAR; PG8_MMA(0, 0, At, B0); PG8_MMA(0, 1, At, B1); PG8_BAR; PG8_SCHED;
	v_mfma_f32_16x16x32_bf16 v[60:63], v[128:131], v[182:185], v[60:63]
	v_mfma_f32_16x16x32_bf16 v[52:55], v[158:161], v[182:185], v[52:55]
	v_mfma_f32_16x16x32_bf16 v[44:47], v[128:131], v[194:197], v[44:47]
	v_mfma_f32_16x16x32_bf16 v[36:39], v[158:161], v[194:197], v[36:39]
	v_mfma_f32_16x16x32_bf16 v[28:31], v[128:131], v[202:205], v[28:31]
	v_mfma_f32_16x16x32_bf16 v[20:23], v[158:161], v[202:205], v[20:23]
	v_mfma_f32_16x16x32_bf16 v[12:15], v[128:131], v[210:213], v[12:15]
	v_mfma_f32_16x16x32_bf16 v[4:7], v[158:161], v[210:213], v[4:7]
	v_mfma_f32_16x16x32_bf16 v[60:63], v[154:157], v[186:189], v[60:63]
	v_mfma_f32_16x16x32_bf16 v[52:55], v[162:165], v[186:189], v[52:55]
	v_mfma_f32_16x16x32_bf16 v[44:47], v[154:157], v[198:201], v[44:47]
	v_mfma_f32_16x16x32_bf16 v[36:39], v[162:165], v[198:201], v[36:39]
	v_mfma_f32_16x16x32_bf16 v[28:31], v[154:157], v[206:209], v[28:31]
	v_mfma_f32_16x16x32_bf16 v[20:23], v[162:165], v[206:209], v[20:23]
	v_mfma_f32_16x16x32_bf16 v[12:15], v[154:157], v[214:217], v[12:15]
	v_mfma_f32_16x16x32_bf16 v[4:7], v[162:165], v[214:217], v[4:7]
	s_setprio 0
	s_setprio 1
	v_mfma_f32_16x16x32_bf16 v[56:59], v[166:169], v[182:185], v[56:59]
	v_mfma_f32_16x16x32_bf16 v[48:51], v[174:177], v[182:185], v[48:51]
	v_mfma_f32_16x16x32_bf16 v[40:43], v[166:169], v[194:197], v[40:43]
	v_mfma_f32_16x16x32_bf16 v[32:35], v[174:177], v[194:197], v[32:35]
	v_mfma_f32_16x16x32_bf16 v[24:27], v[166:169], v[202:205], v[24:27]
	v_mfma_f32_16x16x32_bf16 v[16:19], v[174:177], v[202:205], v[16:19]
	v_mfma_f32_16x16x32_bf16 v[8:11], v[166:169], v[210:213], v[8:11]
	v_mfma_f32_16x16x32_bf16 v[0:3], v[174:177], v[210:213], v[0:3]
	v_mfma_f32_16x16x32_bf16 v[56:59], v[170:173], v[186:189], v[56:59]
	v_mfma_f32_16x16x32_bf16 v[48:51], v[178:181], v[186:189], v[48:51]
	v_mfma_f32_16x16x32_bf16 v[40:43], v[170:173], v[198:201], v[40:43]
	v_mfma_f32_16x16x32_bf16 v[32:35], v[178:181], v[198:201], v[32:35]
	v_mfma_f32_16x16x32_bf16 v[24:27], v[170:173], v[206:209], v[24:27]
	v_mfma_f32_16x16x32_bf16 v[16:19], v[178:181], v[206:209], v[16:19]
	v_mfma_f32_16x16x32_bf16 v[8:11], v[170:173], v[214:217], v[8:11]
	v_mfma_f32_16x16x32_bf16 v[0:3], v[178:181], v[214:217], v[0:3]
	s_barrier
	s_setprio 0
	s_add_i32 s64, 0, 0x18000
	v_add_u32_e32 v146, s64, v149
	s_add_i32 s65, 0, 0x1c000
	ds_read_b128 v[128:131], v146
	ds_read_b128 v[154:157], v146 offset:1024
	ds_read_b128 v[158:161], v146 offset:2048
	ds_read_b128 v[162:165], v146 offset:3072
	v_add_u32_e32 v146, s65, v149
	ds_read_b128 v[166:169], v146
	ds_read_b128 v[170:173], v146 offset:1024
	ds_read_b128 v[174:177], v146 offset:2048
	ds_read_b128 v[178:181], v146 offset:3072
	s_add_u32 s10, s48, 0x40000
	s_addc_u32 s11, s49, 0
	s_mov_b32 m0, s53
	v_lshl_add_u64 v[224:225], s[10:11], 0, v[138:139]
	ds_read_b128 v[182:185], v153 offset:32768
	ds_read_b128 v[186:189], v153 offset:33792
	ds_read_b128 v[194:197], v153 offset:34816
	ds_read_b128 v[198:201], v153 offset:35840
	ds_read_b128 v[202:205], v153 offset:36864
	ds_read_b128 v[206:209], v153 offset:37888
	ds_read_b128 v[210:213], v153 offset:38912
	ds_read_b128 v[214:217], v153 offset:39936
	global_load_lds_dwordx4 v[224:225], off
	v_lshl_add_u64 v[224:225], s[10:11], 0, v[134:135]
	s_mov_b32 m0, s54
	s_nop 0
	global_load_lds_dwordx4 v[224:225], off
	s_waitcnt vmcnt(8)
	s_waitcnt lgkmcnt(0)
	s_setprio 1
	s_barrier
	v_mfma_f32_16x16x32_bf16 v[124:127], v[128:131], v[182:185], v[124:127]
	v_mfma_f32_16x16x32_bf16 v[116:119], v[158:161], v[182:185], v[116:119]
	v_mfma_f32_16x16x32_bf16 v[108:111], v[128:131], v[194:197], v[108:111]
	v_mfma_f32_16x16x32_bf16 v[100:103], v[158:161], v[194:197], v[100:103]
	v_mfma_f32_16x16x32_bf16 v[92:95], v[128:131], v[202:205], v[92:95]
	v_mfma_f32_16x16x32_bf16 v[84:87], v[158:161], v[202:205], v[84:87]
	v_mfma_f32_16x16x32_bf16 v[76:79], v[128:131], v[210:213], v[76:79]
	v_mfma_f32_16x16x32_bf16 v[68:71], v[158:161], v[210:213], v[68:71]
	v_mfma_f32_16x16x32_bf16 v[124:127], v[154:157], v[186:189], v[124:127]
	v_mfma_f32_16x16x32_bf16 v[116:119], v[162:165], v[186:189], v[116:119]
	v_mfma_f32_16x16x32_bf16 v[108:111], v[154:157], v[198:201], v[108:111]
	v_mfma_f32_16x16x32_bf16 v[100:103], v[162:165], v[198:201], v[100:103]
	v_mfma_f32_16x16x32_bf16 v[92:95], v[154:157], v[206:209], v[92:95]
	v_mfma_f32_16x16x32_bf16 v[84:87], v[162:165], v[206:209], v[84:87]
	v_mfma_f32_16x16x32_bf16 v[76:79], v[154:157], v[214:217], v[76:79]
	v_mfma_f32_16x16x32_bf16 v[68:71], v[162:165], v[214:217], v[68:71]
	s_setprio 0
	s_setprio 1
	v_mfma_f32_16x16x32_bf16 v[120:123], v[166:169], v[182:185], v[120:123]
	v_mfma_f32_16x16x32_bf16 v[112:115], v[174:177], v[182:185], v[112:115]
	v_mfma_f32_16x16x32_bf16 v[104:107], v[166:169], v[194:197], v[104:107]
	v_mfma_f32_16x16x32_bf16 v[96:99], v[174:177], v[194:197], v[96:99]
	v_mfma_f32_16x16x32_bf16 v[88:91], v[166:169], v[202:205], v[88:91]
	v_mfma_f32_16x16x32_bf16 v[80:83], v[174:177], v[202:205], v[80:83]
	v_mfma_f32_16x16x32_bf16 v[72:75], v[166:169], v[210:213], v[72:75]
	v_mfma_f32_16x16x32_bf16 v[64:67], v[174:177], v[210:213], v[64:67]
	v_mfma_f32_16x16x32_bf16 v[120:123], v[170:173], v[186:189], v[120:123]
	v_mfma_f32_16x16x32_bf16 v[112:115], v[178:181], v[186:189], v[112:115]
	v_mfma_f32_16x16x32_bf16 v[104:107], v[170:173], v[198:201], v[104:107]
	v_mfma_f32_16x16x32_bf16 v[96:99], v[178:181], v[198:201], v[96:99]
	v_mfma_f32_16x16x32_bf16 v[88:91], v[170:173], v[206:209], v[88:91]
	v_mfma_f32_16x16x32_bf16 v[80:83], v[178:181], v[206:209], v[80:83]
	v_mfma_f32_16x16x32_bf16 v[72:75], v[170:173], v[214:217], v[72:75]
	v_mfma_f32_16x16x32_bf16 v[64:67], v[178:181], v[214:217], v[64:67]
	s_barrier
; #define PG8_STAGE(bufoff, gbase, voff) do { _Pragma("unroll") for (int _i = 0; _i < 2; ++_i) \
;         __builtin_amdgcn_global_load_lds((const unsigned*)((const char*)(gbase) + (voff)[_i]), (PG8_LAS unsigned*)(lds + (bufoff) + ldsw + _i * 8192), 16, 0, 0); } while (0)
; #define PG8_LDA(dst, b, h) do { _Pragma("unroll") for (int m = 0; m < 4; ++m) _Pragma("unroll") for (int k = 0; k < 2; ++k) dst[m][k] = *(const PG8_LAS bf16x8*)(lds + PG8_SA(b, h) + aoff + m * 2048 + k * 1024); } while (0)
; #define PG8_MMA(ai, bj, At, Bt) do { __builtin_amdgcn_s_setprio(1); _Pragma("unroll") for (int m = 0; m < 4; ++m) _Pragma("unroll") for (int n = 0; n < 2; ++n) _Pragma("unroll") for (int k = 0; k < 2; ++k) \
;         acc[ai][bj][m][n] = __builtin_amdgcn_mfma_f32_16x16x32_bf16(Bt[n][k], At[m][k], acc[ai][bj][m][n], 0, 0, 0); __builtin_amdgcn_s_setprio(0); } while (0)
; #define PG8_WAIT_V(n) asm volatile("s_waitcnt vmcnt(" #n ")" ::: "memory")
; #define PG8_WAIT_L(n) asm volatile("s_waitcnt lgkmcnt(" #n ")" ::: "memory")
; #define PG8_BAR __builtin_amdgcn_s_barrier()
; #define PG8_SCHED __builtin_amdgcn_sched_barrier(0)
; template <class Epi, class Sched, bool ALIGN_EPI = false, bool SP2 = false>
; __device__ __forceinline__ void gemm_phase(PG8_LAS unsigned char* lds, const Gemm g, const Sched& S, const Epi& E) {
;     ...
;             PG8_LDA(At, 1, 1); PG8_STAGE(PG8_SB(1, 0), b3, voffB); PG8_STAGE(PG8_SB(1, 1), b3 + hstep, voffB); PG8_STAGE(PG8_SA(1, 0), a3, voffA);
;             PG8_WAIT_V(8); PG8_WAIT_L(0); PG8_BAR; PG8_MMA(1, 0, At, B0); PG8_MMA(1, 1, At, B1); PG8_BAR; PG8_SCHED;
;     ...
;         if constexpr (ALIGN_EPI) { if (wr == 0) PG8_BAR; }
	s_setprio 0
	s_add_i32 s10, s64, s19
	v_lshl_add_u64 v[190:191], v[190:191], 0, s[36:37]
	s_mov_b32 m0, s10
	ds_read_b128 v[182:185], v153 offset:49152
	ds_read_b128 v[186:189], v153 offset:50176
	ds_read_b128 v[194:197], v153 offset:51200
	ds_read_b128 v[198:201], v153 offset:52224
	ds_read_b128 v[202:205], v153 offset:53248
	ds_read_b128 v[206:209], v153 offset:54272
	ds_read_b128 v[210:213], v153 offset:55296
	ds_read_b128 v[214:217], v153 offset:56320
	global_load_lds_dwordx4 v[190:191], off
	s_add_i32 m0, s10, 0x2000
	s_add_u32 s10, s46, 0x40080
	v_lshl_add_u64 v[190:191], v[218:219], 0, s[36:37]
	s_addc_u32 s11, s47, 0
	s_add_i32 s46, s65, s19
	global_load_lds_dwordx4 v[190:191], off
	v_lshl_add_u64 v[190:191], s[10:11], 0, v[136:137]
	s_mov_b32 m0, s46
	s_nop 0
	global_load_lds_dwordx4 v[190:191], off
	v_lshl_add_u64 v[190:191], s[10:11], 0, v[132:133]
	s_add_i32 m0, s46, 0x2000
	s_nop 0
	global_load_lds_dwordx4 v[190:191], off
	v_lshl_add_u64 v[190:191], v[220:221], 0, s[36:37]
	s_mov_b32 m0, s20
	s_nop 0
	global_load_lds_dwordx4 v[190:191], off
	v_lshl_add_u64 v[190:191], v[222:223], 0, s[36:37]
	s_mov_b32 m0, s55
	s_nop 0
	global_load_lds_dwordx4 v[190:191], off
	s_waitcnt vmcnt(8)
	s_waitcnt lgkmcnt(0)
	s_setprio 1
	s_barrier
	v_mfma_f32_16x16x32_bf16 v[60:63], v[128:131], v[182:185], v[60:63]
	v_mfma_f32_16x16x32_bf16 v[52:55], v[158:161], v[182:185], v[52:55]
	v_mfma_f32_16x16x32_bf16 v[44:47], v[128:131], v[194:197], v[44:47]
	v_mfma_f32_16x16x32_bf16 v[36:39], v[158:161], v[194:197], v[36:39]
	v_mfma_f32_16x16x32_bf16 v[28:31], v[128:131], v[202:205], v[28:31]
	v_mfma_f32_16x16x32_bf16 v[20:23], v[158:161], v[202:205], v[20:23]
	v_mfma_f32_16x16x32_bf16 v[12:15], v[128:131], v[210:213], v[12:15]
	v_mfma_f32_16x16x32_bf16 v[4:7], v[158:161], v[210:213], v[4:7]
	v_mfma_f32_16x16x32_bf16 v[60:63], v[154:157], v[186:189], v[60:63]
	v_mfma_f32_16x16x32_bf16 v[52:55], v[162:165], v[186:189], v[52:55]
	v_mfma_f32_16x16x32_bf16 v[44:47], v[154:157], v[198:201], v[44:47]
	v_mfma_f32_16x16x32_bf16 v[36:39], v[162:165], v[198:201], v[36:39]
	v_mfma_f32_16x16x32_bf16 v[28:31], v[154:157], v[206:209], v[28:31]
	v_mfma_f32_16x16x32_bf16 v[20:23], v[162:165], v[206:209], v[20:23]
	v_mfma_f32_16x16x32_bf16 v[12:15], v[154:157], v[214:217], v[12:15]
	v_mfma_f32_16x16x32_bf16 v[4:7], v[162:165], v[214:217], v[4:7]
	s_setprio 0
	s_setprio 1
	v_mfma_f32_16x16x32_bf16 v[56:59], v[166:169], v[182:185], v[56:59]
	v_mfma_f32_16x16x32_bf16 v[48:51], v[174:177], v[182:185], v[48:51]
	v_mfma_f32_16x16x32_bf16 v[40:43], v[166:169], v[194:197], v[40:43]
	v_mfma_f32_16x16x32_bf16 v[32:35], v[174:177], v[194:197], v[32:35]
	v_mfma_f32_16x16x32_bf16 v[24:27], v[166:169], v[202:205], v[24:27]
	v_mfma_f32_16x16x32_bf16 v[16:19], v[174:177], v[202:205], v[16:19]
	v_mfma_f32_16x16x32_bf16 v[8:11], v[166:169], v[210:213], v[8:11]
	v_mfma_f32_16x16x32_bf16 v[0:3], v[174:177], v[210:213], v[0:3]
	v_mfma_f32_16x16x32_bf16 v[56:59], v[170:173], v[186:189], v[56:59]
	v_mfma_f32_16x16x32_bf16 v[48:51], v[178:181], v[186:189], v[48:51]
	v_mfma_f32_16x16x32_bf16 v[40:43], v[170:173], v[198:201], v[40:43]
	v_mfma_f32_16x16x32_bf16 v[32:35], v[178:181], v[198:201], v[32:35]
	v_mfma_f32_16x16x32_bf16 v[24:27], v[170:173], v[206:209], v[24:27]
	v_mfma_f32_16x16x32_bf16 v[16:19], v[178:181], v[206:209], v[16:19]
	v_mfma_f32_16x16x32_bf16 v[8:11], v[170:173], v[214:217], v[8:11]
	v_mfma_f32_16x16x32_bf16 v[0:3], v[178:181], v[214:217], v[0:3]
	s_cbranch_vccnz .Llast2_g4
	s_barrier
	s_setprio 0
	s_add_i32 s63, s63, 2
	s_add_u32 s44, s44, 0x100
	s_addc_u32 s45, s45, 0
	s_add_u32 s61, s61, 0x100
	s_addc_u32 s62, s62, 0
	s_cmp_gt_u32 s63, 13
	s_branch .LBB0_577
.Llast2_g4:
	s_setprio 0
	s_add_i32 s63, s63, 2
	s_add_u32 s44, s44, 0x100
	s_addc_u32 s45, s45, 0
	s_add_u32 s61, s61, 0x100
	s_addc_u32 s62, s62, 0
	s_cmp_gt_u32 s63, 13
	s_and_b64 vcc, exec, s[24:25]
	s_cbranch_vccz .LBB0_580
	s_barrier
